# split-K partial tiles stored as 16 x 16-byte write-through stores (fragment pairs) instead of 32 x 8-byte; reader offsets adjusted; on top of scan-b pipelining and barrier sink
# speedup vs baseline: 1.0026x; 1.0026x over previous
.LBB0_394:
	s_cmp_gt_i32 s54, -1
	s_cbranch_scc0 .LBB0_406
	s_lshl_b32 s8, s38, 3
	s_add_i32 s12, s8, s54
	s_ashr_i32 s13, s12, 31
	s_lshl_b64 s[12:13], s[12:13], 17
	v_mov_b32_e32 v130, v0
	s_add_u32 s12, s62, s12
	s_addc_u32 s13, s63, s13
	v_ashrrev_i32_e32 v131, 31, v130
	v_lshl_add_u64 v[130:131], v[130:131], 4, s[12:13]
	v_cvt_pk_bf16_f32 v132, v126, v127
	v_cvt_pk_bf16_f32 v133, v128, v129
	v_cvt_pk_bf16_f32 v134, v122, v123
	v_cvt_pk_bf16_f32 v135, v124, v125
	global_store_dwordx4 v[130:131], v[132:135], off sc1
	s_nop 1
	v_cvt_pk_bf16_f32 v132, v110, v111
	v_cvt_pk_bf16_f32 v133, v112, v113
	v_cvt_pk_bf16_f32 v134, v106, v107
	v_cvt_pk_bf16_f32 v135, v108, v109
	s_mov_b64 s[98:99], 0x2000
	v_lshl_add_u64 v[136:137], v[130:131], 0, s[98:99]
	global_store_dwordx4 v[136:137], v[132:135], off sc1
	s_nop 1
	v_cvt_pk_bf16_f32 v132, v94, v95
	v_cvt_pk_bf16_f32 v133, v96, v97
	v_cvt_pk_bf16_f32 v134, v90, v91
	v_cvt_pk_bf16_f32 v135, v92, v93
	s_mov_b64 s[98:99], 0x4000
	v_lshl_add_u64 v[136:137], v[130:131], 0, s[98:99]
	global_store_dwordx4 v[136:137], v[132:135], off sc1
	s_nop 1
	v_cvt_pk_bf16_f32 v132, v78, v79
	v_cvt_pk_bf16_f32 v133, v80, v81
	v_cvt_pk_bf16_f32 v134, v74, v75
	v_cvt_pk_bf16_f32 v135, v76, v77
	s_mov_b64 s[98:99], 0x6000
	v_lshl_add_u64 v[136:137], v[130:131], 0, s[98:99]
	global_store_dwordx4 v[136:137], v[132:135], off sc1
	s_nop 1
	v_cvt_pk_bf16_f32 v132, v118, v119
	v_cvt_pk_bf16_f32 v133, v120, v121
	v_cvt_pk_bf16_f32 v134, v114, v115
	v_cvt_pk_bf16_f32 v135, v116, v117
	s_mov_b64 s[98:99], 0x8000
	v_lshl_add_u64 v[136:137], v[130:131], 0, s[98:99]
	global_store_dwordx4 v[136:137], v[132:135], off sc1
	s_nop 1
	v_cvt_pk_bf16_f32 v132, v102, v103
	v_cvt_pk_bf16_f32 v133, v104, v105
	v_cvt_pk_bf16_f32 v134, v98, v99
	v_cvt_pk_bf16_f32 v135, v100, v101
	s_mov_b64 s[98:99], 0xa000
	v_lshl_add_u64 v[136:137], v[130:131], 0, s[98:99]
	global_store_dwordx4 v[136:137], v[132:135], off sc1
	s_nop 1
	v_cvt_pk_bf16_f32 v132, v86, v87
	v_cvt_pk_bf16_f32 v133, v88, v89
	v_cvt_pk_bf16_f32 v134, v82, v83
	v_cvt_pk_bf16_f32 v135, v84, v85
	s_mov_b64 s[98:99], 0xc000
	v_lshl_add_u64 v[136:137], v[130:131], 0, s[98:99]
	global_store_dwordx4 v[136:137], v[132:135], off sc1
	s_nop 1
	v_cvt_pk_bf16_f32 v132, v70, v71
	v_cvt_pk_bf16_f32 v133, v72, v73
	v_cvt_pk_bf16_f32 v134, v66, v67
	v_cvt_pk_bf16_f32 v135, v68, v69
	s_mov_b64 s[98:99], 0xe000
	v_lshl_add_u64 v[136:137], v[130:131], 0, s[98:99]
	global_store_dwordx4 v[136:137], v[132:135], off sc1
	s_nop 1
	v_cvt_pk_bf16_f32 v132, v62, v63
	v_cvt_pk_bf16_f32 v133, v64, v65
	v_cvt_pk_bf16_f32 v134, v58, v59
	v_cvt_pk_bf16_f32 v135, v60, v61
	s_mov_b64 s[98:99], 0x10000
	v_lshl_add_u64 v[136:137], v[130:131], 0, s[98:99]
	global_store_dwordx4 v[136:137], v[132:135], off sc1
	s_nop 1
	v_cvt_pk_bf16_f32 v132, v46, v47
	v_cvt_pk_bf16_f32 v133, v48, v49
	v_cvt_pk_bf16_f32 v134, v42, v43
	v_cvt_pk_bf16_f32 v135, v44, v45
	s_mov_b64 s[98:99], 0x12000
	v_lshl_add_u64 v[136:137], v[130:131], 0, s[98:99]
	global_store_dwordx4 v[136:137], v[132:135], off sc1
	s_nop 1
	v_cvt_pk_bf16_f32 v132, v30, v31
	v_cvt_pk_bf16_f32 v133, v32, v33
	v_cvt_pk_bf16_f32 v134, v26, v27
	v_cvt_pk_bf16_f32 v135, v28, v29
	s_mov_b64 s[98:99], 0x14000
	v_lshl_add_u64 v[136:137], v[130:131], 0, s[98:99]
	global_store_dwordx4 v[136:137], v[132:135], off sc1
	s_nop 1
	v_cvt_pk_bf16_f32 v132, v14, v15
	v_cvt_pk_bf16_f32 v133, v16, v17
	v_cvt_pk_bf16_f32 v134, v10, v11
	v_cvt_pk_bf16_f32 v135, v12, v13
	s_mov_b64 s[98:99], 0x16000
	v_lshl_add_u64 v[136:137], v[130:131], 0, s[98:99]
	global_store_dwordx4 v[136:137], v[132:135], off sc1
	s_nop 1
	v_cvt_pk_bf16_f32 v132, v54, v55
	v_cvt_pk_bf16_f32 v133, v56, v57
	v_cvt_pk_bf16_f32 v134, v50, v51
	v_cvt_pk_bf16_f32 v135, v52, v53
	s_mov_b64 s[98:99], 0x18000
	v_lshl_add_u64 v[136:137], v[130:131], 0, s[98:99]
	global_store_dwordx4 v[136:137], v[132:135], off sc1
	s_nop 1
	v_cvt_pk_bf16_f32 v132, v38, v39
	v_cvt_pk_bf16_f32 v133, v40, v41
	v_cvt_pk_bf16_f32 v134, v34, v35
	v_cvt_pk_bf16_f32 v135, v36, v37
	s_mov_b64 s[98:99], 0x1a000
	v_lshl_add_u64 v[136:137], v[130:131], 0, s[98:99]
	global_store_dwordx4 v[136:137], v[132:135], off sc1
	s_nop 1
	v_cvt_pk_bf16_f32 v132, v22, v23
	v_cvt_pk_bf16_f32 v133, v24, v25
	v_cvt_pk_bf16_f32 v134, v18, v19
	v_cvt_pk_bf16_f32 v135, v20, v21
	s_mov_b64 s[98:99], 0x1c000
	v_lshl_add_u64 v[136:137], v[130:131], 0, s[98:99]
	global_store_dwordx4 v[136:137], v[132:135], off sc1
	s_nop 1
	v_cvt_pk_bf16_f32 v132, v6, v7
	v_cvt_pk_bf16_f32 v133, v8, v9
	v_cvt_pk_bf16_f32 v134, v2, v3
	v_cvt_pk_bf16_f32 v135, v4, v5
	s_mov_b64 s[98:99], 0x1e000
	v_lshl_add_u64 v[136:137], v[130:131], 0, s[98:99]
	global_store_dwordx4 v[136:137], v[132:135], off sc1
	s_nop 1
	s_waitcnt vmcnt(0)
	s_waitcnt vmcnt(0)
	s_barrier
	s_and_saveexec_b64 s[46:47], s[0:1]
	s_cbranch_execz .LBB0_409
	s_lshl_b32 s12, s38, 6
	s_mov_b64 s[50:51], exec
	s_ashr_i32 s13, s12, 31
	s_lshl_b64 s[12:13], s[12:13], 2
	v_mbcnt_lo_u32_b32 v130, s50, 0
	s_add_u32 s48, s83, s12
	v_readlane_b32 s2, v255, 31
	v_mbcnt_hi_u32_b32 v130, s51, v130
	s_addc_u32 s49, s2, s13
	v_cmp_eq_u32_e32 vcc, 0, v130
	s_and_saveexec_b64 s[66:67], vcc
	s_cbranch_execz .LBB0_398
	s_bcnt1_i32_b64 s2, s[50:51]
	v_mov_b32_e32 v130, s2
	global_atomic_add v191, v130, s[48:49]

.LBB0_409:
	s_or_b64 exec, exec, s[46:47]
	s_lshr_b32 s2, s54, 2
	s_and_b32 s33, s54, 3
	v_mov_b32_e32 v130, v0
	s_lshl_b32 s9, s2, 4
	s_lshl_b32 s11, s33, 1
	s_barrier
	s_or_b32 s12, s9, s11
	v_ashrrev_i32_e32 v131, 31, v130
	s_ashr_i32 s9, s8, 31
	v_lshl_add_u64 v[130:131], v[130:131], 4, s[62:63]
	s_or_b32 s40, s12, 8
	s_lshl_b64 s[14:15], s[8:9], 17
	s_mov_b32 s13, s41
	s_lshl_b64 s[46:47], s[40:41], 12
	v_lshl_add_u64 v[132:133], v[130:131], 0, s[14:15]
	s_lshl_b64 s[48:49], s[12:13], 12
	s_or_b32 s40, s12, 1
	v_lshl_add_u64 v[134:135], v[132:133], 0, s[48:49]
	s_add_u32 s50, s48, 8
	s_addc_u32 s51, s49, 0
	s_or_b32 s40, s12, 9
	s_or_b32 s12, s8, 1
	global_load_dwordx2 v[156:157], v[134:135], off sc1
	v_lshl_add_u64 v[134:135], v[132:133], 0, s[50:51]
	s_add_u32 s66, s46, 8
	s_addc_u32 s67, s47, 0
	s_ashr_i32 s13, s12, 31
	global_load_dwordx2 v[158:159], v[134:135], off sc1
	v_lshl_add_u64 v[134:135], v[132:133], 0, s[46:47]
	v_lshl_add_u64 v[132:133], v[132:133], 0, s[66:67]
	s_lshl_b64 s[12:13], s[12:13], 17
	global_load_dwordx2 v[160:161], v[134:135], off sc1
	global_load_dwordx2 v[162:163], v[132:133], off sc1
	v_lshl_add_u64 v[132:133], v[130:131], 0, s[12:13]
	v_lshl_add_u64 v[134:135], v[132:133], 0, s[48:49]
	s_or_b32 s12, s8, 2
	global_load_dwordx2 v[164:165], v[134:135], off sc1
	v_lshl_add_u64 v[134:135], v[132:133], 0, s[50:51]
	s_ashr_i32 s13, s12, 31
	global_load_dwordx2 v[166:167], v[134:135], off sc1
	v_lshl_add_u64 v[134:135], v[132:133], 0, s[46:47]
	v_lshl_add_u64 v[132:133], v[132:133], 0, s[66:67]
	s_lshl_b64 s[12:13], s[12:13], 17
	global_load_dwordx2 v[168:169], v[134:135], off sc1
	global_load_dwordx2 v[170:171], v[132:133], off sc1
	v_lshl_add_u64 v[132:133], v[130:131], 0, s[12:13]
	v_lshl_add_u64 v[134:135], v[132:133], 0, s[48:49]
	s_or_b32 s12, s8, 3
	global_load_dwordx2 v[172:173], v[134:135], off sc1
	v_lshl_add_u64 v[134:135], v[132:133], 0, s[50:51]
	s_ashr_i32 s13, s12, 31
	global_load_dwordx2 v[174:175], v[134:135], off sc1
	v_lshl_add_u64 v[134:135], v[132:133], 0, s[46:47]
	v_lshl_add_u64 v[132:133], v[132:133], 0, s[66:67]
	s_lshl_b64 s[12:13], s[12:13], 17
	global_load_dwordx2 v[176:177], v[134:135], off sc1
	global_load_dwordx2 v[178:179], v[132:133], off sc1
	v_lshl_add_u64 v[132:133], v[130:131], 0, s[12:13]
	v_lshl_add_u64 v[134:135], v[132:133], 0, s[48:49]
	s_or_b32 s12, s8, 4
	global_load_dwordx2 v[180:181], v[134:135], off sc1
	v_lshl_add_u64 v[134:135], v[132:133], 0, s[50:51]
	s_ashr_i32 s13, s12, 31
	global_load_dwordx2 v[182:183], v[134:135], off sc1
	v_lshl_add_u64 v[134:135], v[132:133], 0, s[46:47]
	v_lshl_add_u64 v[132:133], v[132:133], 0, s[66:67]
	s_lshl_b64 s[12:13], s[12:13], 17
	global_load_dwordx2 v[184:185], v[134:135], off sc1
	global_load_dwordx2 v[196:197], v[132:133], off sc1
	v_lshl_add_u64 v[132:133], v[130:131], 0, s[12:13]
	v_lshl_add_u64 v[134:135], v[132:133], 0, s[48:49]
	global_load_dwordx2 v[198:199], v[134:135], off sc1
	v_lshl_add_u64 v[134:135], v[132:133], 0, s[50:51]
	global_load_dwordx2 v[200:201], v[134:135], off sc1
	v_lshl_add_u64 v[134:135], v[132:133], 0, s[46:47]
	global_load_dwordx2 v[202:203], v[134:135], off sc1
	s_or_b32 s12, s8, 5
	s_ashr_i32 s13, s12, 31
	v_lshl_add_u64 v[132:133], v[132:133], 0, s[66:67]
	s_lshl_b64 s[12:13], s[12:13], 17
	global_load_dwordx2 v[152:153], v[132:133], off sc1
	v_lshl_add_u64 v[132:133], v[130:131], 0, s[12:13]
	v_lshl_add_u64 v[134:135], v[132:133], 0, s[48:49]
	global_load_dwordx2 v[154:155], v[134:135], off sc1
	v_lshl_add_u64 v[134:135], v[132:133], 0, s[50:51]
	global_load_dwordx2 v[150:151], v[134:135], off sc1
	v_lshl_add_u64 v[134:135], v[132:133], 0, s[46:47]
	global_load_dwordx2 v[148:149], v[134:135], off sc1
	s_or_b32 s12, s8, 6
	s_ashr_i32 s13, s12, 31
	v_lshl_add_u64 v[132:133], v[132:133], 0, s[66:67]
	s_lshl_b64 s[12:13], s[12:13], 17
	global_load_dwordx2 v[144:145], v[132:133], off sc1
	v_lshl_add_u64 v[132:133], v[130:131], 0, s[12:13]
	v_lshl_add_u64 v[134:135], v[132:133], 0, s[48:49]
	s_or_b32 s8, s8, 7
	global_load_dwordx2 v[146:147], v[134:135], off sc1
	v_lshl_add_u64 v[134:135], v[132:133], 0, s[50:51]
	s_ashr_i32 s9, s8, 31
	global_load_dwordx2 v[142:143], v[134:135], off sc1
	v_lshl_add_u64 v[134:135], v[132:133], 0, s[46:47]
	s_lshl_b64 s[8:9], s[8:9], 17
	s_lshl_b32 s11, s76, 8
	s_waitcnt vmcnt(25)
	v_lshlrev_b32_e32 v204, 16, v156
	v_and_b32_e32 v205, 0xffff0000, v156
	v_lshlrev_b32_e32 v156, 16, v157
	v_and_b32_e32 v157, 0xffff0000, v157
	v_pk_add_f32 v[156:157], v[156:157], 0 op_sel_hi:[1,0]
	s_waitcnt vmcnt(24)
	v_lshlrev_b32_e32 v206, 16, v158
	v_and_b32_e32 v207, 0xffff0000, v158
	v_lshlrev_b32_e32 v158, 16, v159
	v_and_b32_e32 v159, 0xffff0000, v159
	v_pk_add_f32 v[158:159], v[158:159], 0 op_sel_hi:[1,0]
	s_waitcnt vmcnt(23)
	v_lshlrev_b32_e32 v208, 16, v160
	v_and_b32_e32 v209, 0xffff0000, v160
	v_lshlrev_b32_e32 v160, 16, v161
	s_waitcnt vmcnt(21)
	v_lshlrev_b32_e32 v222, 16, v164
	v_and_b32_e32 v223, 0xffff0000, v164
	v_lshlrev_b32_e32 v164, 16, v165
	v_and_b32_e32 v165, 0xffff0000, v165
	v_and_b32_e32 v161, 0xffff0000, v161
	v_pk_add_f32 v[156:157], v[156:157], v[164:165]
	s_waitcnt vmcnt(20)
	v_lshlrev_b32_e32 v164, 16, v166
	v_and_b32_e32 v165, 0xffff0000, v166
	v_lshlrev_b32_e32 v166, 16, v167
	v_and_b32_e32 v167, 0xffff0000, v167
	v_pk_add_f32 v[160:161], v[160:161], 0 op_sel_hi:[1,0]
	v_lshlrev_b32_e32 v210, 16, v162
	v_and_b32_e32 v211, 0xffff0000, v162
	v_lshlrev_b32_e32 v162, 16, v163
	v_and_b32_e32 v163, 0xffff0000, v163
	v_pk_add_f32 v[158:159], v[158:159], v[166:167]
	s_waitcnt vmcnt(19)
	v_lshlrev_b32_e32 v166, 16, v168
	v_and_b32_e32 v167, 0xffff0000, v168
	v_lshlrev_b32_e32 v168, 16, v169
	v_and_b32_e32 v169, 0xffff0000, v169
	v_pk_add_f32 v[162:163], v[162:163], 0 op_sel_hi:[1,0]
	v_pk_add_f32 v[160:161], v[160:161], v[168:169]
	s_waitcnt vmcnt(18)
	v_lshlrev_b32_e32 v168, 16, v170
	v_and_b32_e32 v169, 0xffff0000, v170
	v_lshlrev_b32_e32 v170, 16, v171
	v_and_b32_e32 v171, 0xffff0000, v171
	v_pk_add_f32 v[162:163], v[162:163], v[170:171]
	s_waitcnt vmcnt(17)
	v_lshlrev_b32_e32 v170, 16, v172
	v_and_b32_e32 v171, 0xffff0000, v172
	v_lshlrev_b32_e32 v172, 16, v173
	v_and_b32_e32 v173, 0xffff0000, v173
	v_pk_add_f32 v[156:157], v[156:157], v[172:173]
	s_waitcnt vmcnt(16)
	v_lshlrev_b32_e32 v172, 16, v174
	v_and_b32_e32 v173, 0xffff0000, v174
	v_lshlrev_b32_e32 v174, 16, v175
	v_and_b32_e32 v175, 0xffff0000, v175
	v_pk_add_f32 v[206:207], v[206:207], 0 op_sel_hi:[1,0]
	v_pk_add_f32 v[158:159], v[158:159], v[174:175]
	s_waitcnt vmcnt(15)
	v_lshlrev_b32_e32 v174, 16, v177
	v_and_b32_e32 v175, 0xffff0000, v177
	v_pk_add_f32 v[208:209], v[208:209], 0 op_sel_hi:[1,0]
	v_pk_add_f32 v[164:165], v[206:207], v[164:165]
	v_pk_add_f32 v[160:161], v[160:161], v[174:175]
	s_waitcnt vmcnt(14)
	v_lshlrev_b32_e32 v174, 16, v179
	v_and_b32_e32 v175, 0xffff0000, v179
	v_pk_add_f32 v[204:205], v[204:205], 0 op_sel_hi:[1,0]
	v_pk_add_f32 v[210:211], v[210:211], 0 op_sel_hi:[1,0]
	v_pk_add_f32 v[166:167], v[208:209], v[166:167]
	v_pk_add_f32 v[164:165], v[164:165], v[172:173]
	v_lshlrev_b32_e32 v172, 16, v176
	v_and_b32_e32 v173, 0xffff0000, v176
	v_pk_add_f32 v[162:163], v[162:163], v[174:175]
	s_waitcnt vmcnt(13)
	v_lshlrev_b32_e32 v174, 16, v181
	v_and_b32_e32 v175, 0xffff0000, v181
	v_pk_add_f32 v[204:205], v[204:205], v[222:223]
	v_pk_add_f32 v[168:169], v[210:211], v[168:169]
	v_pk_add_f32 v[166:167], v[166:167], v[172:173]
	v_lshlrev_b32_e32 v172, 16, v178
	v_and_b32_e32 v173, 0xffff0000, v178
	v_pk_add_f32 v[156:157], v[156:157], v[174:175]
	s_waitcnt vmcnt(12)
	v_lshlrev_b32_e32 v174, 16, v183
	v_and_b32_e32 v175, 0xffff0000, v183
	v_pk_add_f32 v[170:171], v[204:205], v[170:171]
	v_pk_add_f32 v[168:169], v[168:169], v[172:173]
	v_lshlrev_b32_e32 v172, 16, v180
	v_and_b32_e32 v173, 0xffff0000, v180
	v_pk_add_f32 v[158:159], v[158:159], v[174:175]
	s_waitcnt vmcnt(11)
	v_lshlrev_b32_e32 v174, 16, v185
	v_and_b32_e32 v175, 0xffff0000, v185
	v_pk_add_f32 v[170:171], v[170:171], v[172:173]
	v_lshlrev_b32_e32 v172, 16, v182
	v_and_b32_e32 v173, 0xffff0000, v182
	v_pk_add_f32 v[160:161], v[160:161], v[174:175]
	s_waitcnt vmcnt(10)
	v_lshlrev_b32_e32 v174, 16, v197
	v_and_b32_e32 v175, 0xffff0000, v197
	v_pk_add_f32 v[164:165], v[164:165], v[172:173]
	v_lshlrev_b32_e32 v172, 16, v184
	v_and_b32_e32 v173, 0xffff0000, v184
	v_pk_add_f32 v[162:163], v[162:163], v[174:175]
	s_waitcnt vmcnt(9)
	v_lshlrev_b32_e32 v174, 16, v199
	v_and_b32_e32 v175, 0xffff0000, v199
	v_pk_add_f32 v[166:167], v[166:167], v[172:173]
	v_lshlrev_b32_e32 v172, 16, v196
	v_and_b32_e32 v173, 0xffff0000, v196
	v_pk_add_f32 v[174:175], v[156:157], v[174:175]
	s_waitcnt vmcnt(8)
	v_lshlrev_b32_e32 v156, 16, v200
	v_and_b32_e32 v157, 0xffff0000, v200
	v_pk_add_f32 v[168:169], v[168:169], v[172:173]
	v_lshlrev_b32_e32 v172, 16, v198
	v_and_b32_e32 v173, 0xffff0000, v198
	v_pk_add_f32 v[164:165], v[164:165], v[156:157]
	s_waitcnt vmcnt(7)
	v_lshlrev_b32_e32 v156, 16, v202
	v_and_b32_e32 v157, 0xffff0000, v202
	v_pk_add_f32 v[170:171], v[170:171], v[172:173]
	v_lshlrev_b32_e32 v172, 16, v201
	v_and_b32_e32 v173, 0xffff0000, v201
	v_pk_add_f32 v[166:167], v[166:167], v[156:157]
	v_lshl_add_u32 v156, s2, 7, v215
	global_load_dwordx2 v[140:141], v[134:135], off sc1
	v_lshl_add_u64 v[132:133], v[132:133], 0, s[66:67]
	v_lshl_add_u64 v[130:131], v[130:131], 0, s[8:9]
	v_pk_add_f32 v[172:173], v[158:159], v[172:173]
	v_lshlrev_b32_e32 v158, 16, v203
	v_and_b32_e32 v159, 0xffff0000, v203
	s_lshl_b32 s33, s33, 4
	v_add_u32_e32 v157, s11, v156
	global_load_dwordx2 v[136:137], v[132:133], off sc1
	v_lshl_add_u64 v[132:133], v[130:131], 0, s[48:49]
	v_pk_add_f32 v[176:177], v[160:161], v[158:159]
	v_or_b32_e32 v158, s33, v157
	global_load_dwordx2 v[138:139], v[132:133], off sc1
	v_lshl_add_u64 v[132:133], v[130:131], 0, s[50:51]
	v_ashrrev_i32_e32 v159, 31, v158
	v_readlane_b32 s8, v254, 62
	global_load_dwordx2 v[134:135], v[132:133], off sc1
	v_lshl_add_u64 v[132:133], v[130:131], 0, s[46:47]
	v_lshl_or_b32 v160, s10, 8, v217
	v_lshlrev_b64 v[158:159], 11, v[158:159]
	v_readlane_b32 s9, v254, 63
	global_load_dwordx2 v[132:133], v[132:133], off sc1
	v_lshl_add_u64 v[130:131], v[130:131], 0, s[66:67]
	v_ashrrev_i32_e32 v161, 31, v160
	v_lshl_add_u64 v[158:159], s[8:9], 0, v[158:159]
	global_load_dwordx2 v[130:131], v[130:131], off sc1
	v_lshl_add_u64 v[178:179], v[160:161], 1, v[158:159]
	global_load_dwordx4 v[158:161], v[178:179], off
	s_waitcnt vmcnt(13)
	v_lshlrev_b32_e32 v180, 16, v152
	v_and_b32_e32 v181, 0xffff0000, v152
	v_lshlrev_b32_e32 v152, 16, v153
	v_and_b32_e32 v153, 0xffff0000, v153
	v_pk_add_f32 v[152:153], v[162:163], v[152:153]
	v_pk_add_f32 v[162:163], v[168:169], v[180:181]
	s_waitcnt vmcnt(12)
	v_lshlrev_b32_e32 v168, 16, v154
	v_and_b32_e32 v169, 0xffff0000, v154
	v_pk_add_f32 v[168:169], v[170:171], v[168:169]
	s_waitcnt vmcnt(11)
	v_lshlrev_b32_e32 v170, 16, v150
	v_and_b32_e32 v171, 0xffff0000, v150
	v_lshlrev_b32_e32 v150, 16, v151
	v_and_b32_e32 v151, 0xffff0000, v151
	v_pk_add_f32 v[164:165], v[164:165], v[170:171]
	v_pk_add_f32 v[170:171], v[172:173], v[150:151]
	s_waitcnt vmcnt(10)
	v_lshlrev_b32_e32 v150, 16, v148
	v_and_b32_e32 v151, 0xffff0000, v148
	v_lshlrev_b32_e32 v148, 16, v149
	v_and_b32_e32 v149, 0xffff0000, v149
	v_pk_add_f32 v[166:167], v[166:167], v[150:151]
	v_pk_add_f32 v[172:173], v[176:177], v[148:149]
	global_load_dwordx4 v[148:151], v[178:179], off offset:256
	v_lshlrev_b32_e32 v154, 16, v155
	v_and_b32_e32 v155, 0xffff0000, v155
	v_pk_add_f32 v[154:155], v[174:175], v[154:155]
	s_waitcnt vmcnt(10)
	v_lshlrev_b32_e32 v174, 16, v144
	v_and_b32_e32 v175, 0xffff0000, v144
	v_lshlrev_b32_e32 v144, 16, v145
	v_and_b32_e32 v145, 0xffff0000, v145
	v_pk_add_f32 v[144:145], v[152:153], v[144:145]
	s_waitcnt vmcnt(9)
	v_lshlrev_b32_e32 v152, 16, v146
	v_and_b32_e32 v153, 0xffff0000, v146
	v_lshlrev_b32_e32 v146, 16, v147
	v_and_b32_e32 v147, 0xffff0000, v147
	v_pk_add_f32 v[146:147], v[154:155], v[146:147]
	s_waitcnt vmcnt(8)
	v_lshlrev_b32_e32 v154, 16, v142
	v_and_b32_e32 v155, 0xffff0000, v142
	v_pk_add_f32 v[154:155], v[164:165], v[154:155]
	v_pk_add_f32 v[162:163], v[162:163], v[174:175]
	v_lshlrev_b32_e32 v142, 16, v143
	v_and_b32_e32 v143, 0xffff0000, v143
	v_pk_add_f32 v[142:143], v[170:171], v[142:143]
	v_pk_add_f32 v[152:153], v[168:169], v[152:153]
	s_waitcnt vmcnt(7)
	v_lshlrev_b32_e32 v164, 16, v140
	v_and_b32_e32 v165, 0xffff0000, v140
	v_pk_add_f32 v[164:165], v[166:167], v[164:165]
	v_lshlrev_b32_e32 v140, 16, v141
	v_and_b32_e32 v141, 0xffff0000, v141
	v_pk_add_f32 v[140:141], v[172:173], v[140:141]
	s_waitcnt vmcnt(6)
	v_lshlrev_b32_e32 v166, 16, v136
	v_and_b32_e32 v167, 0xffff0000, v136
	v_lshlrev_b32_e32 v136, 16, v137
	v_and_b32_e32 v137, 0xffff0000, v137
	v_pk_add_f32 v[136:137], v[144:145], v[136:137]
	v_pk_add_f32 v[144:145], v[162:163], v[166:167]
	s_waitcnt vmcnt(5)
	v_lshlrev_b32_e32 v162, 16, v138
	v_and_b32_e32 v163, 0xffff0000, v138
	v_lshlrev_b32_e32 v138, 16, v139
	v_and_b32_e32 v139, 0xffff0000, v139
	v_pk_add_f32 v[138:139], v[146:147], v[138:139]
	s_waitcnt vmcnt(4)
	v_lshlrev_b32_e32 v146, 16, v134
	v_and_b32_e32 v147, 0xffff0000, v134
	v_lshlrev_b32_e32 v134, 16, v135
	v_and_b32_e32 v135, 0xffff0000, v135
	v_pk_add_f32 v[134:135], v[142:143], v[134:135]
	s_waitcnt vmcnt(3)
	v_lshlrev_b32_e32 v142, 16, v132
	v_and_b32_e32 v143, 0xffff0000, v132
	v_lshlrev_b32_e32 v132, 16, v133
	v_and_b32_e32 v133, 0xffff0000, v133
	v_pk_add_f32 v[132:133], v[140:141], v[132:133]
	s_waitcnt vmcnt(2)
	v_lshlrev_b32_e32 v140, 16, v130
	v_and_b32_e32 v141, 0xffff0000, v130
	v_lshlrev_b32_e32 v130, 16, v131
	v_and_b32_e32 v131, 0xffff0000, v131
	v_pk_add_f32 v[152:153], v[152:153], v[162:163]
	v_pk_add_f32 v[140:141], v[144:145], v[140:141]
	v_pk_add_f32 v[136:137], v[136:137], v[130:131]
	s_waitcnt vmcnt(1)
	v_lshlrev_b32_e32 v130, 16, v158
	v_and_b32_e32 v131, 0xffff0000, v158
	v_lshlrev_b32_e32 v144, 16, v159
	v_and_b32_e32 v145, 0xffff0000, v159
	v_pk_add_f32 v[146:147], v[154:155], v[146:147]
	v_lshlrev_b32_e32 v154, 16, v160
	v_and_b32_e32 v155, 0xffff0000, v160
	v_pk_fma_f32 v[138:139], v[138:139], 0.5, v[144:145] op_sel_hi:[1,0,1]
	v_pk_fma_f32 v[130:131], v[152:153], 0.5, v[130:131] op_sel_hi:[1,0,1]
	v_lshlrev_b32_e32 v158, 16, v161
	v_and_b32_e32 v159, 0xffff0000, v161
	v_pk_fma_f32 v[144:145], v[146:147], 0.5, v[154:155] op_sel_hi:[1,0,1]
	v_mul_f32_e32 v146, v131, v131
	v_mul_f32_e32 v147, v139, v139
	v_pk_fma_f32 v[134:135], v[134:135], 0.5, v[158:159] op_sel_hi:[1,0,1]
	v_fmac_f32_e32 v146, v130, v130
	v_fmac_f32_e32 v147, v138, v138
	v_add_f32_e32 v146, v146, v147
	v_mul_f32_e32 v147, v145, v145
	v_mul_f32_e32 v152, v135, v135
	v_fmac_f32_e32 v147, v144, v144
	v_fmac_f32_e32 v152, v134, v134
	v_add_f32_e32 v147, v147, v152
	v_pk_add_f32 v[142:143], v[164:165], v[142:143]
	v_add_f32_e32 v152, v146, v147
	v_cvt_pk_bf16_f32 v130, v130, v131
	v_cvt_pk_bf16_f32 v131, v138, v139
	s_waitcnt vmcnt(0)
	v_lshlrev_b32_e32 v138, 16, v148
	v_and_b32_e32 v139, 0xffff0000, v148
	v_lshlrev_b32_e32 v146, 16, v149
	v_and_b32_e32 v147, 0xffff0000, v149
	v_pk_fma_f32 v[146:147], v[132:133], 0.5, v[146:147] op_sel_hi:[1,0,1]
	v_pk_fma_f32 v[138:139], v[142:143], 0.5, v[138:139] op_sel_hi:[1,0,1]
	v_lshlrev_b32_e32 v148, 16, v150
	v_and_b32_e32 v149, 0xffff0000, v150
	v_lshlrev_b32_e32 v150, 16, v151
	v_and_b32_e32 v151, 0xffff0000, v151
	v_mul_f32_e32 v132, v139, v139
	v_mul_f32_e32 v133, v147, v147
	v_pk_fma_f32 v[136:137], v[136:137], 0.5, v[150:151] op_sel_hi:[1,0,1]
	v_pk_fma_f32 v[140:141], v[140:141], 0.5, v[148:149] op_sel_hi:[1,0,1]
	v_fmac_f32_e32 v132, v138, v138
	v_fmac_f32_e32 v133, v146, v146
	v_add_f32_e32 v132, v132, v133
	v_mul_f32_e32 v133, v141, v141
	v_mul_f32_e32 v142, v137, v137
	v_fmac_f32_e32 v133, v140, v140
	v_fmac_f32_e32 v142, v136, v136
	v_add_f32_e32 v133, v133, v142
	v_add_f32_e32 v132, v132, v133
	v_and_b32_e32 v133, 64, v221
	v_add_f32_e32 v142, v152, v132
	v_xor_b32_e32 v132, 16, v221
	v_add_u32_e32 v143, 64, v133
	v_cmp_lt_i32_e32 vcc, v132, v143
	s_nop 1
	v_cndmask_b32_e32 v132, v221, v132, vcc
	v_lshlrev_b32_e32 v132, 2, v132
	ds_bpermute_b32 v148, v132, v142
	v_cvt_pk_bf16_f32 v132, v144, v145
	v_cvt_pk_bf16_f32 v133, v134, v135
	global_store_dwordx4 v[178:179], v[130:133], off
	s_nop 1
	v_xor_b32_e32 v131, 32, v221
	v_cmp_lt_i32_e32 vcc, v131, v143
	s_waitcnt lgkmcnt(0)
	v_add_f32_e32 v130, v142, v148
	v_cvt_pk_bf16_f32 v132, v138, v139
	v_cvt_pk_bf16_f32 v133, v146, v147
	v_cvt_pk_bf16_f32 v134, v140, v141
	v_cvt_pk_bf16_f32 v135, v136, v137
	v_cndmask_b32_e32 v131, v221, v131, vcc
	v_lshlrev_b32_e32 v131, 2, v131
	ds_bpermute_b32 v131, v131, v130
	global_store_dwordx4 v[178:179], v[132:135], off offset:256
	s_and_saveexec_b64 s[8:9], s[6:7]
	s_cbranch_execz .LBB0_411
	v_or_b32_e32 v132, s33, v156
	v_lshl_add_u32 v132, v132, 4, s42
	s_waitcnt lgkmcnt(0)
	v_add_f32_e32 v130, v130, v131
	ds_write_b32 v132, v130

.LBB0_980:
	s_cmp_gt_i32 s53, -1
	s_mov_b64 s[46:47], -1
	s_cbranch_scc0 .LBB0_992
	s_lshl_b32 s46, s3, 3
	s_add_i32 s12, s46, s53
	s_ashr_i32 s13, s12, 31
	s_lshl_b64 s[12:13], s[12:13], 17
	v_mov_b32_e32 v130, v0
	s_add_u32 s12, s68, s12
	s_addc_u32 s13, s69, s13
	v_ashrrev_i32_e32 v131, 31, v130
	v_lshl_add_u64 v[130:131], v[130:131], 4, s[12:13]
	v_cvt_pk_bf16_f32 v144, v126, v127
	v_cvt_pk_bf16_f32 v145, v128, v129
	v_cvt_pk_bf16_f32 v146, v122, v123
	v_cvt_pk_bf16_f32 v147, v124, v125
	global_store_dwordx4 v[130:131], v[144:147], off sc1
	s_nop 1
	v_cvt_pk_bf16_f32 v144, v110, v111
	v_cvt_pk_bf16_f32 v145, v112, v113
	v_cvt_pk_bf16_f32 v146, v106, v107
	v_cvt_pk_bf16_f32 v147, v108, v109
	s_mov_b64 s[98:99], 0x2000
	v_lshl_add_u64 v[142:143], v[130:131], 0, s[98:99]
	global_store_dwordx4 v[142:143], v[144:147], off sc1
	s_nop 1
	v_cvt_pk_bf16_f32 v144, v94, v95
	v_cvt_pk_bf16_f32 v145, v96, v97
	v_cvt_pk_bf16_f32 v146, v90, v91
	v_cvt_pk_bf16_f32 v147, v92, v93
	s_mov_b64 s[98:99], 0x4000
	v_lshl_add_u64 v[142:143], v[130:131], 0, s[98:99]
	global_store_dwordx4 v[142:143], v[144:147], off sc1
	s_nop 1
	v_cvt_pk_bf16_f32 v144, v78, v79
	v_cvt_pk_bf16_f32 v145, v80, v81
	v_cvt_pk_bf16_f32 v146, v70, v71
	v_cvt_pk_bf16_f32 v147, v72, v73
	s_mov_b64 s[98:99], 0x6000
	v_lshl_add_u64 v[142:143], v[130:131], 0, s[98:99]
	global_store_dwordx4 v[142:143], v[144:147], off sc1
	s_nop 1
	v_cvt_pk_bf16_f32 v144, v118, v119
	v_cvt_pk_bf16_f32 v145, v120, v121
	v_cvt_pk_bf16_f32 v146, v114, v115
	v_cvt_pk_bf16_f32 v147, v116, v117
	s_mov_b64 s[98:99], 0x8000
	v_lshl_add_u64 v[142:143], v[130:131], 0, s[98:99]
	global_store_dwordx4 v[142:143], v[144:147], off sc1
	s_nop 1
	v_cvt_pk_bf16_f32 v144, v102, v103
	v_cvt_pk_bf16_f32 v145, v104, v105
	v_cvt_pk_bf16_f32 v146, v98, v99
	v_cvt_pk_bf16_f32 v147, v100, v101
	s_mov_b64 s[98:99], 0xa000
	v_lshl_add_u64 v[142:143], v[130:131], 0, s[98:99]
	global_store_dwordx4 v[142:143], v[144:147], off sc1
	s_nop 1
	v_cvt_pk_bf16_f32 v144, v86, v87
	v_cvt_pk_bf16_f32 v145, v88, v89
	v_cvt_pk_bf16_f32 v146, v82, v83
	v_cvt_pk_bf16_f32 v147, v84, v85
	s_mov_b64 s[98:99], 0xc000
	v_lshl_add_u64 v[142:143], v[130:131], 0, s[98:99]
	global_store_dwordx4 v[142:143], v[144:147], off sc1
	s_nop 1
	v_cvt_pk_bf16_f32 v144, v66, v67
	v_cvt_pk_bf16_f32 v145, v68, v69
	v_cvt_pk_bf16_f32 v146, v54, v55
	v_cvt_pk_bf16_f32 v147, v56, v57
	s_mov_b64 s[98:99], 0xe000
	v_lshl_add_u64 v[142:143], v[130:131], 0, s[98:99]
	global_store_dwordx4 v[142:143], v[144:147], off sc1
	s_nop 1
	v_cvt_pk_bf16_f32 v144, v74, v75
	v_cvt_pk_bf16_f32 v145, v76, v77
	v_cvt_pk_bf16_f32 v146, v62, v63
	v_cvt_pk_bf16_f32 v147, v64, v65
	s_mov_b64 s[98:99], 0x10000
	v_lshl_add_u64 v[142:143], v[130:131], 0, s[98:99]
	global_store_dwordx4 v[142:143], v[144:147], off sc1
	s_nop 1
	v_cvt_pk_bf16_f32 v144, v46, v47
	v_cvt_pk_bf16_f32 v145, v48, v49
	v_cvt_pk_bf16_f32 v146, v42, v43
	v_cvt_pk_bf16_f32 v147, v44, v45
	s_mov_b64 s[98:99], 0x12000
	v_lshl_add_u64 v[142:143], v[130:131], 0, s[98:99]
	global_store_dwordx4 v[142:143], v[144:147], off sc1
	s_nop 1
	v_cvt_pk_bf16_f32 v144, v30, v31
	v_cvt_pk_bf16_f32 v145, v32, v33
	v_cvt_pk_bf16_f32 v146, v26, v27
	v_cvt_pk_bf16_f32 v147, v28, v29
	s_mov_b64 s[98:99], 0x14000
	v_lshl_add_u64 v[142:143], v[130:131], 0, s[98:99]
	global_store_dwordx4 v[142:143], v[144:147], off sc1
	s_nop 1
	v_cvt_pk_bf16_f32 v144, v14, v15
	v_cvt_pk_bf16_f32 v145, v16, v17
	v_cvt_pk_bf16_f32 v146, v10, v11
	v_cvt_pk_bf16_f32 v147, v12, v13
	s_mov_b64 s[98:99], 0x16000
	v_lshl_add_u64 v[142:143], v[130:131], 0, s[98:99]
	global_store_dwordx4 v[142:143], v[144:147], off sc1
	s_nop 1
	v_cvt_pk_bf16_f32 v144, v58, v59
	v_cvt_pk_bf16_f32 v145, v60, v61
	v_cvt_pk_bf16_f32 v146, v50, v51
	v_cvt_pk_bf16_f32 v147, v52, v53
	s_mov_b64 s[98:99], 0x18000
	v_lshl_add_u64 v[142:143], v[130:131], 0, s[98:99]
	global_store_dwordx4 v[142:143], v[144:147], off sc1
	s_nop 1
	v_cvt_pk_bf16_f32 v144, v38, v39
	v_cvt_pk_bf16_f32 v145, v40, v41
	v_cvt_pk_bf16_f32 v146, v34, v35
	v_cvt_pk_bf16_f32 v147, v36, v37
	s_mov_b64 s[98:99], 0x1a000
	v_lshl_add_u64 v[142:143], v[130:131], 0, s[98:99]
	global_store_dwordx4 v[142:143], v[144:147], off sc1
	s_nop 1
	v_cvt_pk_bf16_f32 v144, v22, v23
	v_cvt_pk_bf16_f32 v145, v24, v25
	v_cvt_pk_bf16_f32 v146, v18, v19
	v_cvt_pk_bf16_f32 v147, v20, v21
	s_mov_b64 s[98:99], 0x1c000
	v_lshl_add_u64 v[142:143], v[130:131], 0, s[98:99]
	global_store_dwordx4 v[142:143], v[144:147], off sc1
	s_nop 1
	v_cvt_pk_bf16_f32 v144, v6, v7
	v_cvt_pk_bf16_f32 v145, v8, v9
	v_cvt_pk_bf16_f32 v146, v2, v3
	v_cvt_pk_bf16_f32 v147, v4, v5
	s_mov_b64 s[98:99], 0x1e000
	v_lshl_add_u64 v[142:143], v[130:131], 0, s[98:99]
	global_store_dwordx4 v[142:143], v[144:147], off sc1
	s_nop 1
	s_waitcnt vmcnt(0)
	s_waitcnt vmcnt(0)
	s_barrier
	s_and_saveexec_b64 s[48:49], s[0:1]
	s_cbranch_execz .LBB0_994
	s_lshl_b32 s12, s3, 6
	s_mov_b64 s[66:67], exec
	s_ashr_i32 s13, s12, 31
	s_lshl_b64 s[12:13], s[12:13], 2
	v_readlane_b32 s2, v255, 31
	v_mbcnt_lo_u32_b32 v130, s66, 0
	s_add_u32 s50, s2, s12
	v_readlane_b32 s2, v255, 33
	v_mbcnt_hi_u32_b32 v130, s67, v130
	s_addc_u32 s51, s2, s13
	v_cmp_eq_u32_e32 vcc, 0, v130
	s_and_saveexec_b64 s[12:13], vcc
	s_cbranch_execz .LBB0_984
	s_bcnt1_i32_b64 s2, s[66:67]
	v_mov_b32_e32 v130, s2
	global_atomic_add v137, v130, s[50:51]

.LBB0_994:
	s_or_b64 exec, exec, s[48:49]
	s_lshr_b32 s12, s53, 2
	s_and_b32 s2, s53, 3
	v_mov_b32_e32 v130, v0
	s_lshl_b32 s13, s12, 4
	s_lshl_b32 s14, s2, 1
	s_barrier
	s_or_b32 s14, s13, s14
	v_ashrrev_i32_e32 v131, 31, v130
	s_ashr_i32 s47, s46, 31
	v_lshl_add_u64 v[130:131], v[130:131], 4, s[68:69]
	s_or_b32 s58, s14, 8
	s_lshl_b64 s[16:17], s[46:47], 17
	s_mov_b32 s15, s59
	s_lshl_b64 s[48:49], s[58:59], 12
	v_lshl_add_u64 v[132:133], v[130:131], 0, s[16:17]
	s_lshl_b64 s[50:51], s[14:15], 12
	s_or_b32 s58, s14, 1
	v_lshl_add_u64 v[142:143], v[132:133], 0, s[50:51]
	s_add_u32 s66, s50, 8
	s_addc_u32 s67, s51, 0
	s_or_b32 s58, s14, 9
	s_or_b32 s14, s46, 1
	global_load_dwordx2 v[164:165], v[142:143], off sc1
	v_lshl_add_u64 v[142:143], v[132:133], 0, s[66:67]
	s_add_u32 vcc_lo, s48, 8
	s_addc_u32 vcc_hi, s49, 0
	s_ashr_i32 s15, s14, 31
	global_load_dwordx2 v[166:167], v[142:143], off sc1
	v_lshl_add_u64 v[142:143], v[132:133], 0, s[48:49]
	v_lshl_add_u64 v[132:133], v[132:133], 0, vcc
	s_lshl_b64 s[14:15], s[14:15], 17
	global_load_dwordx2 v[176:177], v[142:143], off sc1
	global_load_dwordx2 v[178:179], v[132:133], off sc1
	v_lshl_add_u64 v[132:133], v[130:131], 0, s[14:15]
	v_lshl_add_u64 v[142:143], v[132:133], 0, s[50:51]
	s_or_b32 s14, s46, 2
	global_load_dwordx2 v[180:181], v[142:143], off sc1
	v_lshl_add_u64 v[142:143], v[132:133], 0, s[66:67]
	s_ashr_i32 s15, s14, 31
	global_load_dwordx2 v[182:183], v[142:143], off sc1
	v_lshl_add_u64 v[142:143], v[132:133], 0, s[48:49]
	v_lshl_add_u64 v[132:133], v[132:133], 0, vcc
	s_lshl_b64 s[14:15], s[14:15], 17
	global_load_dwordx2 v[184:185], v[142:143], off sc1
	global_load_dwordx2 v[188:189], v[132:133], off sc1
	v_lshl_add_u64 v[132:133], v[130:131], 0, s[14:15]
	v_lshl_add_u64 v[142:143], v[132:133], 0, s[50:51]
	s_or_b32 s14, s46, 3
	global_load_dwordx2 v[190:191], v[142:143], off sc1
	v_lshl_add_u64 v[142:143], v[132:133], 0, s[66:67]
	s_ashr_i32 s15, s14, 31
	global_load_dwordx2 v[192:193], v[142:143], off sc1
	v_lshl_add_u64 v[142:143], v[132:133], 0, s[48:49]
	v_lshl_add_u64 v[132:133], v[132:133], 0, vcc
	s_lshl_b64 s[14:15], s[14:15], 17
	global_load_dwordx2 v[194:195], v[142:143], off sc1
	global_load_dwordx2 v[198:199], v[132:133], off sc1
	v_lshl_add_u64 v[132:133], v[130:131], 0, s[14:15]
	v_lshl_add_u64 v[142:143], v[132:133], 0, s[50:51]
	s_or_b32 s14, s46, 4
	global_load_dwordx2 v[200:201], v[142:143], off sc1
	v_lshl_add_u64 v[142:143], v[132:133], 0, s[66:67]
	s_ashr_i32 s15, s14, 31
	global_load_dwordx2 v[202:203], v[142:143], off sc1
	v_lshl_add_u64 v[142:143], v[132:133], 0, s[48:49]
	v_lshl_add_u64 v[132:133], v[132:133], 0, vcc
	s_lshl_b64 s[14:15], s[14:15], 17
	global_load_dwordx2 v[204:205], v[142:143], off sc1
	global_load_dwordx2 v[206:207], v[132:133], off sc1
	v_lshl_add_u64 v[132:133], v[130:131], 0, s[14:15]
	v_lshl_add_u64 v[142:143], v[132:133], 0, s[50:51]
	global_load_dwordx2 v[208:209], v[142:143], off sc1
	v_lshl_add_u64 v[142:143], v[132:133], 0, s[66:67]
	global_load_dwordx2 v[210:211], v[142:143], off sc1
	v_lshl_add_u64 v[142:143], v[132:133], 0, s[48:49]
	global_load_dwordx2 v[212:213], v[142:143], off sc1
	s_or_b32 s14, s46, 5
	s_ashr_i32 s15, s14, 31
	v_lshl_add_u64 v[132:133], v[132:133], 0, vcc
	s_lshl_b64 s[14:15], s[14:15], 17
	global_load_dwordx2 v[160:161], v[132:133], off sc1
	v_lshl_add_u64 v[132:133], v[130:131], 0, s[14:15]
	v_lshl_add_u64 v[142:143], v[132:133], 0, s[50:51]
	global_load_dwordx2 v[162:163], v[142:143], off sc1
	s_or_b32 s14, s46, 6
	v_lshl_add_u64 v[142:143], v[132:133], 0, s[66:67]
	s_ashr_i32 s15, s14, 31
	global_load_dwordx2 v[158:159], v[142:143], off sc1
	v_lshl_add_u64 v[142:143], v[132:133], 0, s[48:49]
	v_lshl_add_u64 v[132:133], v[132:133], 0, vcc
	s_lshl_b64 s[14:15], s[14:15], 17
	global_load_dwordx2 v[156:157], v[142:143], off sc1
	global_load_dwordx2 v[152:153], v[132:133], off sc1
	v_lshl_add_u64 v[132:133], v[130:131], 0, s[14:15]
	v_lshl_add_u64 v[142:143], v[132:133], 0, s[50:51]
	s_or_b32 s14, s46, 7
	global_load_dwordx2 v[154:155], v[142:143], off sc1
	v_lshl_add_u64 v[142:143], v[132:133], 0, s[66:67]
	s_ashr_i32 s15, s14, 31
	s_lshl_b32 s13, s26, 8
	s_lshl_b32 s12, s12, 7
	global_load_dwordx2 v[150:151], v[142:143], off sc1
	v_lshl_add_u64 v[142:143], v[132:133], 0, s[48:49]
	s_waitcnt vmcnt(25)
	v_lshlrev_b32_e32 v214, 16, v164
	v_and_b32_e32 v215, 0xffff0000, v164
	v_lshlrev_b32_e32 v164, 16, v165
	v_and_b32_e32 v165, 0xffff0000, v165
	v_pk_add_f32 v[214:215], v[214:215], 0 op_sel_hi:[1,0]
	v_pk_add_f32 v[164:165], v[164:165], 0 op_sel_hi:[1,0]
	s_waitcnt vmcnt(24)
	v_lshlrev_b32_e32 v216, 16, v166
	v_and_b32_e32 v217, 0xffff0000, v166
	v_lshlrev_b32_e32 v166, 16, v167
	v_and_b32_e32 v167, 0xffff0000, v167
	v_pk_add_f32 v[216:217], v[216:217], 0 op_sel_hi:[1,0]
	v_pk_add_f32 v[166:167], v[166:167], 0 op_sel_hi:[1,0]
	s_waitcnt vmcnt(23)
	v_lshlrev_b32_e32 v218, 16, v176
	s_waitcnt vmcnt(21)
	v_lshlrev_b32_e32 v222, 16, v180
	v_and_b32_e32 v223, 0xffff0000, v180
	v_lshlrev_b32_e32 v180, 16, v181
	v_and_b32_e32 v181, 0xffff0000, v181
	v_and_b32_e32 v219, 0xffff0000, v176
	v_lshlrev_b32_e32 v176, 16, v177
	v_and_b32_e32 v177, 0xffff0000, v177
	v_pk_add_f32 v[164:165], v[164:165], v[180:181]
	v_pk_add_f32 v[180:181], v[214:215], v[222:223]
	s_waitcnt vmcnt(20)
	v_lshlrev_b32_e32 v214, 16, v182
	v_and_b32_e32 v215, 0xffff0000, v182
	v_lshlrev_b32_e32 v182, 16, v183
	v_and_b32_e32 v183, 0xffff0000, v183
	v_pk_add_f32 v[218:219], v[218:219], 0 op_sel_hi:[1,0]
	v_pk_add_f32 v[176:177], v[176:177], 0 op_sel_hi:[1,0]
	v_lshlrev_b32_e32 v220, 16, v178
	v_and_b32_e32 v221, 0xffff0000, v178
	v_lshlrev_b32_e32 v178, 16, v179
	v_and_b32_e32 v179, 0xffff0000, v179
	v_pk_add_f32 v[166:167], v[166:167], v[182:183]
	v_pk_add_f32 v[182:183], v[216:217], v[214:215]
	s_waitcnt vmcnt(19)
	v_lshlrev_b32_e32 v214, 16, v184
	v_and_b32_e32 v215, 0xffff0000, v184
	v_lshlrev_b32_e32 v184, 16, v185
	v_and_b32_e32 v185, 0xffff0000, v185
	v_pk_add_f32 v[220:221], v[220:221], 0 op_sel_hi:[1,0]
	v_pk_add_f32 v[178:179], v[178:179], 0 op_sel_hi:[1,0]
	v_pk_add_f32 v[176:177], v[176:177], v[184:185]
	v_pk_add_f32 v[184:185], v[218:219], v[214:215]
	s_waitcnt vmcnt(18)
	v_lshlrev_b32_e32 v214, 16, v188
	v_and_b32_e32 v215, 0xffff0000, v188
	v_lshlrev_b32_e32 v188, 16, v189
	v_and_b32_e32 v189, 0xffff0000, v189
	v_pk_add_f32 v[178:179], v[178:179], v[188:189]
	v_pk_add_f32 v[188:189], v[220:221], v[214:215]
	s_waitcnt vmcnt(17)
	v_lshlrev_b32_e32 v214, 16, v190
	v_and_b32_e32 v215, 0xffff0000, v190
	v_lshlrev_b32_e32 v190, 16, v191
	v_and_b32_e32 v191, 0xffff0000, v191
	v_pk_add_f32 v[164:165], v[164:165], v[190:191]
	s_waitcnt vmcnt(16)
	v_lshlrev_b32_e32 v190, 16, v192
	v_and_b32_e32 v191, 0xffff0000, v192
	v_lshlrev_b32_e32 v192, 16, v193
	v_and_b32_e32 v193, 0xffff0000, v193
	v_pk_add_f32 v[166:167], v[166:167], v[192:193]
	s_waitcnt vmcnt(15)
	v_lshlrev_b32_e32 v192, 16, v195
	v_and_b32_e32 v193, 0xffff0000, v195
	v_pk_add_f32 v[176:177], v[176:177], v[192:193]
	s_waitcnt vmcnt(14)
	v_lshlrev_b32_e32 v192, 16, v199
	v_and_b32_e32 v193, 0xffff0000, v199
	v_pk_add_f32 v[178:179], v[178:179], v[192:193]
	s_waitcnt vmcnt(13)
	v_lshlrev_b32_e32 v192, 16, v201
	v_and_b32_e32 v193, 0xffff0000, v201
	v_pk_add_f32 v[164:165], v[164:165], v[192:193]
	s_waitcnt vmcnt(12)
	v_lshlrev_b32_e32 v192, 16, v203
	v_and_b32_e32 v193, 0xffff0000, v203
	v_pk_add_f32 v[166:167], v[166:167], v[192:193]
	s_waitcnt vmcnt(11)
	v_lshlrev_b32_e32 v192, 16, v205
	v_and_b32_e32 v193, 0xffff0000, v205
	v_pk_add_f32 v[176:177], v[176:177], v[192:193]
	s_waitcnt vmcnt(10)
	v_lshlrev_b32_e32 v192, 16, v207
	v_and_b32_e32 v193, 0xffff0000, v207
	v_pk_add_f32 v[178:179], v[178:179], v[192:193]
	s_waitcnt vmcnt(9)
	v_lshlrev_b32_e32 v192, 16, v209
	v_and_b32_e32 v193, 0xffff0000, v209
	s_lshl_b64 s[14:15], s[14:15], 17
	v_pk_add_f32 v[164:165], v[164:165], v[192:193]
	s_waitcnt vmcnt(8)
	v_lshlrev_b32_e32 v192, 16, v211
	v_and_b32_e32 v193, 0xffff0000, v211
	s_add_i32 s12, s12, s13
	global_load_dwordx2 v[148:149], v[142:143], off sc1
	v_lshl_add_u64 v[132:133], v[132:133], 0, vcc
	v_lshl_add_u64 v[130:131], v[130:131], 0, s[14:15]
	v_pk_add_f32 v[166:167], v[166:167], v[192:193]
	s_waitcnt vmcnt(8)
	v_lshlrev_b32_e32 v192, 16, v213
	v_and_b32_e32 v193, 0xffff0000, v213
	v_add_u32_e32 v175, s12, v169
	global_load_dwordx2 v[144:145], v[132:133], off sc1
	v_lshl_add_u64 v[132:133], v[130:131], 0, s[50:51]
	v_pk_add_f32 v[176:177], v[176:177], v[192:193]
	v_lshl_or_b32 v192, s2, 4, v175
	global_load_dwordx2 v[146:147], v[132:133], off sc1
	v_lshl_add_u64 v[132:133], v[130:131], 0, s[66:67]
	v_pk_add_f32 v[182:183], v[182:183], v[190:191]
	v_lshlrev_b32_e32 v190, 16, v194
	v_and_b32_e32 v191, 0xffff0000, v194
	v_ashrrev_i32_e32 v193, 31, v192
	global_load_dwordx2 v[142:143], v[132:133], off sc1
	v_lshl_add_u64 v[132:133], v[130:131], 0, s[48:49]
	v_pk_add_f32 v[184:185], v[184:185], v[190:191]
	v_lshlrev_b32_e32 v190, 16, v198
	v_and_b32_e32 v191, 0xffff0000, v198
	v_lshl_or_b32 v194, s24, 8, v171
	v_lshlrev_b64 v[198:199], 10, v[192:193]
	global_load_dwordx2 v[132:133], v[132:133], off sc1
	v_lshl_add_u64 v[130:131], v[130:131], 0, vcc
	v_lshl_add_u64 v[198:199], s[20:21], 0, v[198:199]
	v_ashrrev_i32_e32 v195, 31, v194
	global_load_dwordx2 v[130:131], v[130:131], off sc1
	v_lshl_add_u64 v[198:199], v[198:199], 0, v[194:195]
	v_pk_add_f32 v[188:189], v[188:189], v[190:191]
	v_lshlrev_b32_e32 v190, 16, v200
	v_and_b32_e32 v191, 0xffff0000, v200
	global_load_dwordx2 v[200:201], v[198:199], off
	v_pk_add_f32 v[180:181], v[180:181], v[214:215]
	v_readlane_b32 s12, v255, 0
	v_pk_add_f32 v[180:181], v[180:181], v[190:191]
	v_lshlrev_b32_e32 v190, 16, v202
	v_and_b32_e32 v191, 0xffff0000, v202
	v_pk_add_f32 v[182:183], v[182:183], v[190:191]
	v_lshlrev_b32_e32 v190, 16, v204
	v_and_b32_e32 v191, 0xffff0000, v204
	v_pk_add_f32 v[184:185], v[184:185], v[190:191]
	v_lshlrev_b32_e32 v190, 16, v206
	v_and_b32_e32 v191, 0xffff0000, v206
	v_pk_add_f32 v[188:189], v[188:189], v[190:191]
	v_lshlrev_b32_e32 v190, 16, v208
	v_and_b32_e32 v191, 0xffff0000, v208
	v_pk_add_f32 v[180:181], v[180:181], v[190:191]
	v_lshlrev_b32_e32 v190, 16, v210
	v_and_b32_e32 v191, 0xffff0000, v210
	v_pk_add_f32 v[182:183], v[182:183], v[190:191]
	v_lshlrev_b32_e32 v190, 16, v212
	v_and_b32_e32 v191, 0xffff0000, v212
	v_pk_add_f32 v[184:185], v[184:185], v[190:191]
	s_waitcnt vmcnt(13)
	v_lshlrev_b32_e32 v190, 16, v160
	v_and_b32_e32 v191, 0xffff0000, v160
	v_lshlrev_b32_e32 v160, 16, v161
	v_and_b32_e32 v161, 0xffff0000, v161
	v_pk_add_f32 v[160:161], v[178:179], v[160:161]
	s_waitcnt vmcnt(12)
	v_lshlrev_b32_e32 v178, 16, v162
	v_and_b32_e32 v179, 0xffff0000, v162
	v_lshlrev_b32_e32 v162, 16, v163
	v_and_b32_e32 v163, 0xffff0000, v163
	v_pk_add_f32 v[162:163], v[164:165], v[162:163]
	v_pk_add_f32 v[164:165], v[180:181], v[178:179]
	global_load_dwordx2 v[180:181], v[198:199], off offset:128
	s_waitcnt vmcnt(12)
	v_lshlrev_b32_e32 v178, 16, v158
	v_and_b32_e32 v179, 0xffff0000, v158
	v_lshlrev_b32_e32 v158, 16, v159
	v_and_b32_e32 v159, 0xffff0000, v159
	v_pk_add_f32 v[158:159], v[166:167], v[158:159]
	v_pk_add_f32 v[166:167], v[182:183], v[178:179]
	s_waitcnt vmcnt(11)
	v_lshlrev_b32_e32 v178, 16, v156
	v_and_b32_e32 v179, 0xffff0000, v156
	v_lshlrev_b32_e32 v156, 16, v157
	v_and_b32_e32 v157, 0xffff0000, v157
	v_pk_add_f32 v[188:189], v[188:189], v[190:191]
	v_pk_add_f32 v[156:157], v[176:177], v[156:157]
	v_pk_add_f32 v[176:177], v[184:185], v[178:179]
	s_waitcnt vmcnt(10)
	v_lshlrev_b32_e32 v178, 16, v152
	v_and_b32_e32 v179, 0xffff0000, v152
	v_lshlrev_b32_e32 v152, 16, v153
	v_and_b32_e32 v153, 0xffff0000, v153
	v_pk_add_f32 v[152:153], v[160:161], v[152:153]
	v_pk_add_f32 v[160:161], v[188:189], v[178:179]
	s_waitcnt vmcnt(9)
	v_lshlrev_b32_e32 v178, 16, v154
	v_and_b32_e32 v179, 0xffff0000, v154
	v_lshlrev_b32_e32 v154, 16, v155
	v_and_b32_e32 v155, 0xffff0000, v155
	v_pk_add_f32 v[154:155], v[162:163], v[154:155]
	s_waitcnt vmcnt(8)
	v_lshlrev_b32_e32 v162, 16, v150
	v_and_b32_e32 v163, 0xffff0000, v150
	v_lshlrev_b32_e32 v150, 16, v151
	v_and_b32_e32 v151, 0xffff0000, v151
	v_pk_add_f32 v[150:151], v[158:159], v[150:151]
	s_waitcnt vmcnt(7)
	v_lshlrev_b32_e32 v158, 16, v148
	v_and_b32_e32 v159, 0xffff0000, v148
	v_lshlrev_b32_e32 v148, 16, v149
	v_and_b32_e32 v149, 0xffff0000, v149
	v_pk_add_f32 v[148:149], v[156:157], v[148:149]
	s_waitcnt vmcnt(6)
	v_lshlrev_b32_e32 v156, 16, v144
	v_and_b32_e32 v157, 0xffff0000, v144
	v_lshlrev_b32_e32 v144, 16, v145
	v_and_b32_e32 v145, 0xffff0000, v145
	v_pk_add_f32 v[144:145], v[152:153], v[144:145]
	s_waitcnt vmcnt(5)
	v_lshlrev_b32_e32 v152, 16, v146
	v_and_b32_e32 v153, 0xffff0000, v146
	v_lshlrev_b32_e32 v146, 16, v147
	v_and_b32_e32 v147, 0xffff0000, v147
	v_pk_add_f32 v[162:163], v[166:167], v[162:163]
	v_pk_add_f32 v[146:147], v[154:155], v[146:147]
	s_waitcnt vmcnt(4)
	v_lshlrev_b32_e32 v154, 16, v142
	v_and_b32_e32 v155, 0xffff0000, v142
	v_lshlrev_b32_e32 v142, 16, v143
	v_and_b32_e32 v143, 0xffff0000, v143
	v_pk_add_f32 v[142:143], v[150:151], v[142:143]
	v_pk_add_f32 v[150:151], v[162:163], v[154:155]
	s_waitcnt vmcnt(3)
	v_lshlrev_b32_e32 v154, 16, v132
	v_and_b32_e32 v155, 0xffff0000, v132
	v_lshlrev_b32_e32 v132, 16, v133
	v_and_b32_e32 v133, 0xffff0000, v133
	v_pk_add_f32 v[158:159], v[176:177], v[158:159]
	v_pk_add_f32 v[148:149], v[148:149], v[132:133]
	s_waitcnt vmcnt(2)
	v_lshlrev_b32_e32 v132, 16, v130
	v_and_b32_e32 v133, 0xffff0000, v130
	v_lshlrev_b32_e32 v130, 16, v131
	v_and_b32_e32 v131, 0xffff0000, v131
	v_pk_add_f32 v[164:165], v[164:165], v[178:179]
	v_pk_add_f32 v[154:155], v[158:159], v[154:155]
	v_pk_add_f32 v[158:159], v[144:145], v[130:131]
	s_waitcnt vmcnt(1)
	v_cvt_f32_ubyte0_e32 v130, v200
	v_cvt_f32_ubyte1_e32 v131, v200
	v_pk_add_f32 v[152:153], v[164:165], v[152:153]
	v_mul_f32_e32 v130, 0x3b808081, v130
	v_mul_f32_e32 v131, 0x3b808081, v131
	v_pk_add_f32 v[156:157], v[160:161], v[156:157]
	v_mul_f32_e32 v130, v130, v152
	v_mul_f32_e32 v131, v131, v153
	v_pk_add_f32 v[156:157], v[156:157], v[132:133]
	v_cvt_pk_bf16_f32 v130, v130, v131
	v_cvt_f32_ubyte2_e32 v131, v200
	v_cvt_f32_ubyte3_e32 v132, v200
	v_mul_f32_e32 v131, 0x3b808081, v131
	v_mul_f32_e32 v132, 0x3b808081, v132
	v_mul_f32_e32 v131, v131, v146
	v_mul_f32_e32 v132, v132, v147
	v_cvt_pk_bf16_f32 v131, v131, v132
	v_cvt_f32_ubyte0_e32 v132, v201
	v_cvt_f32_ubyte1_e32 v133, v201
	v_mul_f32_e32 v132, 0x3b808081, v132
	v_mul_f32_e32 v133, 0x3b808081, v133
	v_mul_f32_e32 v132, v132, v150
	v_mul_f32_e32 v133, v133, v151
	v_cvt_pk_bf16_f32 v132, v132, v133
	v_cvt_f32_ubyte2_e32 v133, v201
	v_mul_f32_e32 v133, 0x3b808081, v133
	v_mul_f32_e32 v133, v133, v142
	v_cvt_f32_ubyte3_e32 v142, v201
	v_mul_f32_e32 v142, 0x3b808081, v142
	v_lshlrev_b64 v[144:145], 11, v[192:193]
	v_mul_f32_e32 v142, v142, v143
	v_readlane_b32 s13, v255, 1
	v_cvt_pk_bf16_f32 v133, v133, v142
	s_nop 1
	v_lshl_add_u64 v[142:143], s[12:13], 0, v[144:145]
	v_lshl_add_u64 v[144:145], v[194:195], 1, v[142:143]
	global_store_dwordx4 v[144:145], v[130:133], off
	s_waitcnt vmcnt(1)
	v_cvt_f32_ubyte3_e32 v142, v181
	v_mul_f32_e32 v142, 0x3b808081, v142
	v_cvt_f32_ubyte0_e32 v130, v180
	v_cvt_f32_ubyte1_e32 v131, v180
	v_mul_f32_e32 v130, 0x3b808081, v130
	v_mul_f32_e32 v131, 0x3b808081, v131
	v_mul_f32_e32 v130, v130, v154
	v_mul_f32_e32 v131, v131, v155
	v_cvt_pk_bf16_f32 v130, v130, v131
	v_cvt_f32_ubyte2_e32 v131, v180
	v_cvt_f32_ubyte3_e32 v132, v180
	v_mul_f32_e32 v131, 0x3b808081, v131
	v_mul_f32_e32 v132, 0x3b808081, v132
	v_mul_f32_e32 v131, v131, v148
	v_mul_f32_e32 v132, v132, v149
	v_cvt_pk_bf16_f32 v131, v131, v132
	v_cvt_f32_ubyte0_e32 v132, v181
	v_cvt_f32_ubyte1_e32 v133, v181
	v_mul_f32_e32 v132, 0x3b808081, v132
	v_mul_f32_e32 v133, 0x3b808081, v133
	v_mul_f32_e32 v132, v132, v156
	v_mul_f32_e32 v133, v133, v157
	v_cvt_pk_bf16_f32 v132, v132, v133
	v_cvt_f32_ubyte2_e32 v133, v181
	v_mul_f32_e32 v133, 0x3b808081, v133
	v_mul_f32_e32 v133, v133, v158
	v_mul_f32_e32 v142, v142, v159
	v_cvt_pk_bf16_f32 v133, v133, v142

.LBB0_1340:
	s_cmp_gt_i32 s53, -1
	s_mov_b64 s[50:51], -1
	s_cbranch_scc0 .LBB0_1352
	s_lshl_b32 s50, s52, 3
	s_add_i32 s0, s50, s53
	s_ashr_i32 s1, s0, 31
	s_lshl_b64 s[0:1], s[0:1], 17
	v_mov_b32_e32 v130, v0
	s_add_u32 s0, s68, s0
	s_addc_u32 s1, s69, s1
	v_ashrrev_i32_e32 v131, 31, v130
	v_lshl_add_u64 v[130:131], v[130:131], 4, s[0:1]
	v_cvt_pk_bf16_f32 v132, v118, v119
	v_cvt_pk_bf16_f32 v133, v120, v121
	v_cvt_pk_bf16_f32 v134, v114, v115
	v_cvt_pk_bf16_f32 v135, v116, v117
	global_store_dwordx4 v[130:131], v[132:135], off sc1
	s_nop 1
	v_cvt_pk_bf16_f32 v132, v102, v103
	v_cvt_pk_bf16_f32 v133, v104, v105
	v_cvt_pk_bf16_f32 v134, v98, v99
	v_cvt_pk_bf16_f32 v135, v100, v101
	s_mov_b64 s[98:99], 0x2000
	v_lshl_add_u64 v[136:137], v[130:131], 0, s[98:99]
	global_store_dwordx4 v[136:137], v[132:135], off sc1
	s_nop 1
	v_cvt_pk_bf16_f32 v132, v86, v87
	v_cvt_pk_bf16_f32 v133, v88, v89
	v_cvt_pk_bf16_f32 v134, v82, v83
	v_cvt_pk_bf16_f32 v135, v84, v85
	s_mov_b64 s[98:99], 0x4000
	v_lshl_add_u64 v[136:137], v[130:131], 0, s[98:99]
	global_store_dwordx4 v[136:137], v[132:135], off sc1
	s_nop 1
	v_cvt_pk_bf16_f32 v132, v62, v63
	v_cvt_pk_bf16_f32 v133, v64, v65
	v_cvt_pk_bf16_f32 v134, v58, v59
	v_cvt_pk_bf16_f32 v135, v60, v61
	s_mov_b64 s[98:99], 0x6000
	v_lshl_add_u64 v[136:137], v[130:131], 0, s[98:99]
	global_store_dwordx4 v[136:137], v[132:135], off sc1
	s_nop 1
	v_cvt_pk_bf16_f32 v132, v126, v127
	v_cvt_pk_bf16_f32 v133, v128, v129
	v_cvt_pk_bf16_f32 v134, v122, v123
	v_cvt_pk_bf16_f32 v135, v124, v125
	s_mov_b64 s[98:99], 0x8000
	v_lshl_add_u64 v[136:137], v[130:131], 0, s[98:99]
	global_store_dwordx4 v[136:137], v[132:135], off sc1
	s_nop 1
	v_cvt_pk_bf16_f32 v132, v110, v111
	v_cvt_pk_bf16_f32 v133, v112, v113
	v_cvt_pk_bf16_f32 v134, v106, v107
	v_cvt_pk_bf16_f32 v135, v108, v109
	s_mov_b64 s[98:99], 0xa000
	v_lshl_add_u64 v[136:137], v[130:131], 0, s[98:99]
	global_store_dwordx4 v[136:137], v[132:135], off sc1
	s_nop 1
	v_cvt_pk_bf16_f32 v132, v94, v95
	v_cvt_pk_bf16_f32 v133, v96, v97
	v_cvt_pk_bf16_f32 v134, v90, v91
	v_cvt_pk_bf16_f32 v135, v92, v93
	s_mov_b64 s[98:99], 0xc000
	v_lshl_add_u64 v[136:137], v[130:131], 0, s[98:99]
	global_store_dwordx4 v[136:137], v[132:135], off sc1
	s_nop 1
	v_cvt_pk_bf16_f32 v132, v78, v79
	v_cvt_pk_bf16_f32 v133, v80, v81
	v_cvt_pk_bf16_f32 v134, v74, v75
	v_cvt_pk_bf16_f32 v135, v76, v77
	s_mov_b64 s[98:99], 0xe000
	v_lshl_add_u64 v[136:137], v[130:131], 0, s[98:99]
	global_store_dwordx4 v[136:137], v[132:135], off sc1
	s_nop 1
	v_cvt_pk_bf16_f32 v132, v54, v55
	v_cvt_pk_bf16_f32 v133, v56, v57
	v_cvt_pk_bf16_f32 v134, v50, v51
	v_cvt_pk_bf16_f32 v135, v52, v53
	s_mov_b64 s[98:99], 0x10000
	v_lshl_add_u64 v[136:137], v[130:131], 0, s[98:99]
	global_store_dwordx4 v[136:137], v[132:135], off sc1
	s_nop 1
	v_cvt_pk_bf16_f32 v132, v38, v39
	v_cvt_pk_bf16_f32 v133, v40, v41
	v_cvt_pk_bf16_f32 v134, v34, v35
	v_cvt_pk_bf16_f32 v135, v36, v37
	s_mov_b64 s[98:99], 0x12000
	v_lshl_add_u64 v[136:137], v[130:131], 0, s[98:99]
	global_store_dwordx4 v[136:137], v[132:135], off sc1
	s_nop 1
	v_cvt_pk_bf16_f32 v132, v22, v23
	v_cvt_pk_bf16_f32 v133, v24, v25
	v_cvt_pk_bf16_f32 v134, v18, v19
	v_cvt_pk_bf16_f32 v135, v20, v21
	s_mov_b64 s[98:99], 0x14000
	v_lshl_add_u64 v[136:137], v[130:131], 0, s[98:99]
	global_store_dwordx4 v[136:137], v[132:135], off sc1
	s_nop 1
	v_cvt_pk_bf16_f32 v132, v6, v7
	v_cvt_pk_bf16_f32 v133, v8, v9
	v_cvt_pk_bf16_f32 v134, v2, v3
	v_cvt_pk_bf16_f32 v135, v4, v5
	s_mov_b64 s[98:99], 0x16000
	v_lshl_add_u64 v[136:137], v[130:131], 0, s[98:99]
	global_store_dwordx4 v[136:137], v[132:135], off sc1
	s_nop 1
	v_cvt_pk_bf16_f32 v132, v70, v71
	v_cvt_pk_bf16_f32 v133, v72, v73
	v_cvt_pk_bf16_f32 v134, v66, v67
	v_cvt_pk_bf16_f32 v135, v68, v69
	s_mov_b64 s[98:99], 0x18000
	v_lshl_add_u64 v[136:137], v[130:131], 0, s[98:99]
	global_store_dwordx4 v[136:137], v[132:135], off sc1
	s_nop 1
	v_cvt_pk_bf16_f32 v132, v46, v47
	v_cvt_pk_bf16_f32 v133, v48, v49
	v_cvt_pk_bf16_f32 v134, v42, v43
	v_cvt_pk_bf16_f32 v135, v44, v45
	s_mov_b64 s[98:99], 0x1a000
	v_lshl_add_u64 v[136:137], v[130:131], 0, s[98:99]
	global_store_dwordx4 v[136:137], v[132:135], off sc1
	s_nop 1
	v_cvt_pk_bf16_f32 v132, v30, v31
	v_cvt_pk_bf16_f32 v133, v32, v33
	v_cvt_pk_bf16_f32 v134, v26, v27
	v_cvt_pk_bf16_f32 v135, v28, v29
	s_mov_b64 s[98:99], 0x1c000
	v_lshl_add_u64 v[136:137], v[130:131], 0, s[98:99]
	global_store_dwordx4 v[136:137], v[132:135], off sc1
	s_nop 1
	v_cvt_pk_bf16_f32 v132, v14, v15
	v_cvt_pk_bf16_f32 v133, v16, v17
	v_cvt_pk_bf16_f32 v134, v10, v11
	v_cvt_pk_bf16_f32 v135, v12, v13
	s_mov_b64 s[98:99], 0x1e000
	v_lshl_add_u64 v[136:137], v[130:131], 0, s[98:99]
	global_store_dwordx4 v[136:137], v[132:135], off sc1
	s_nop 1
	s_waitcnt vmcnt(0)
	s_waitcnt vmcnt(0)
	s_barrier
	s_mov_b64 s[88:89], exec
	v_readlane_b32 s0, v255, 29
	v_readlane_b32 s1, v255, 30
	s_and_b64 s[0:1], s[88:89], s[0:1]
	s_mov_b64 exec, s[0:1]
	s_cbranch_execz .LBB0_1357
	s_lshl_b32 s0, s52, 6
	s_mov_b64 s[92:93], exec
	s_ashr_i32 s1, s0, 31
	s_lshl_b64 s[0:1], s[0:1], 2
	v_readlane_b32 s3, v255, 31
	v_mbcnt_lo_u32_b32 v130, s92, 0
	s_add_u32 s90, s3, s0
	v_readlane_b32 s0, v255, 33
	v_mbcnt_hi_u32_b32 v130, s93, v130
	s_addc_u32 s91, s0, s1
	v_cmp_eq_u32_e32 vcc, 0, v130
	s_and_saveexec_b64 s[94:95], vcc
	s_cbranch_execz .LBB0_1344
	s_bcnt1_i32_b64 s0, s[92:93]
	v_mov_b32_e32 v130, s0
	global_atomic_add v153, v130, s[90:91]

.LBB0_1357:
	s_or_b64 exec, exec, s[88:89]
	s_lshr_b32 s1, s53, 2
	s_and_b32 s0, s53, 3
	v_mov_b32_e32 v130, v0
	s_lshl_b32 s3, s1, 4
	s_lshl_b32 s18, s0, 1
	s_barrier
	s_or_b32 s18, s3, s18
	v_ashrrev_i32_e32 v131, 31, v130
	s_ashr_i32 s51, s50, 31
	v_lshl_add_u64 v[130:131], v[130:131], 4, s[68:69]
	s_or_b32 s46, s18, 8
	s_lshl_b64 s[20:21], s[50:51], 17
	s_mov_b32 s19, s47
	s_lshl_b64 s[88:89], s[46:47], 12
	v_lshl_add_u64 v[132:133], v[130:131], 0, s[20:21]
	s_lshl_b64 s[90:91], s[18:19], 12
	s_or_b32 s46, s18, 1
	v_lshl_add_u64 v[134:135], v[132:133], 0, s[90:91]
	s_add_u32 s92, s90, 8
	s_addc_u32 s93, s91, 0
	s_or_b32 s46, s18, 9
	s_or_b32 s18, s50, 1
	global_load_dwordx2 v[158:159], v[134:135], off sc1
	v_lshl_add_u64 v[134:135], v[132:133], 0, s[92:93]
	s_add_u32 s94, s88, 8
	s_addc_u32 s95, s89, 0
	s_ashr_i32 s19, s18, 31
	global_load_dwordx2 v[160:161], v[134:135], off sc1
	v_lshl_add_u64 v[134:135], v[132:133], 0, s[88:89]
	v_lshl_add_u64 v[132:133], v[132:133], 0, s[94:95]
	s_lshl_b64 s[18:19], s[18:19], 17
	global_load_dwordx2 v[168:169], v[134:135], off sc1
	global_load_dwordx2 v[170:171], v[132:133], off sc1
	v_lshl_add_u64 v[132:133], v[130:131], 0, s[18:19]
	v_lshl_add_u64 v[134:135], v[132:133], 0, s[90:91]
	s_or_b32 s18, s50, 2
	global_load_dwordx2 v[172:173], v[134:135], off sc1
	v_lshl_add_u64 v[134:135], v[132:133], 0, s[92:93]
	s_ashr_i32 s19, s18, 31
	global_load_dwordx2 v[174:175], v[134:135], off sc1
	v_lshl_add_u64 v[134:135], v[132:133], 0, s[88:89]
	v_lshl_add_u64 v[132:133], v[132:133], 0, s[94:95]
	s_lshl_b64 s[18:19], s[18:19], 17
	global_load_dwordx2 v[176:177], v[134:135], off sc1
	global_load_dwordx2 v[178:179], v[132:133], off sc1
	v_lshl_add_u64 v[132:133], v[130:131], 0, s[18:19]
	v_lshl_add_u64 v[134:135], v[132:133], 0, s[90:91]
	s_or_b32 s18, s50, 3
	global_load_dwordx2 v[180:181], v[134:135], off sc1
	v_lshl_add_u64 v[134:135], v[132:133], 0, s[92:93]
	s_ashr_i32 s19, s18, 31
	global_load_dwordx2 v[182:183], v[134:135], off sc1
	v_lshl_add_u64 v[134:135], v[132:133], 0, s[88:89]
	v_lshl_add_u64 v[132:133], v[132:133], 0, s[94:95]
	s_lshl_b64 s[18:19], s[18:19], 17
	global_load_dwordx2 v[194:195], v[134:135], off sc1
	global_load_dwordx2 v[196:197], v[132:133], off sc1
	v_lshl_add_u64 v[132:133], v[130:131], 0, s[18:19]
	v_lshl_add_u64 v[134:135], v[132:133], 0, s[90:91]
	s_or_b32 s18, s50, 4
	global_load_dwordx2 v[198:199], v[134:135], off sc1
	v_lshl_add_u64 v[134:135], v[132:133], 0, s[92:93]
	s_ashr_i32 s19, s18, 31
	global_load_dwordx2 v[200:201], v[134:135], off sc1
	v_lshl_add_u64 v[134:135], v[132:133], 0, s[88:89]
	v_lshl_add_u64 v[132:133], v[132:133], 0, s[94:95]
	s_lshl_b64 s[18:19], s[18:19], 17
	global_load_dwordx2 v[202:203], v[134:135], off sc1
	global_load_dwordx2 v[204:205], v[132:133], off sc1
	v_lshl_add_u64 v[132:133], v[130:131], 0, s[18:19]
	v_lshl_add_u64 v[134:135], v[132:133], 0, s[90:91]
	global_load_dwordx2 v[206:207], v[134:135], off sc1
	v_lshl_add_u64 v[134:135], v[132:133], 0, s[92:93]
	global_load_dwordx2 v[208:209], v[134:135], off sc1
	v_lshl_add_u64 v[134:135], v[132:133], 0, s[88:89]
	global_load_dwordx2 v[210:211], v[134:135], off sc1
	v_lshl_add_u64 v[132:133], v[132:133], 0, s[94:95]
	global_load_dwordx2 v[164:165], v[132:133], off sc1
	s_or_b32 s18, s50, 5
	s_ashr_i32 s19, s18, 31
	s_lshl_b64 s[18:19], s[18:19], 17
	v_lshl_add_u64 v[132:133], v[130:131], 0, s[18:19]
	v_lshl_add_u64 v[134:135], v[132:133], 0, s[90:91]
	s_or_b32 s18, s50, 6
	global_load_dwordx2 v[166:167], v[134:135], off sc1
	v_lshl_add_u64 v[134:135], v[132:133], 0, s[92:93]
	s_ashr_i32 s19, s18, 31
	global_load_dwordx2 v[162:163], v[134:135], off sc1
	v_lshl_add_u64 v[134:135], v[132:133], 0, s[88:89]
	v_lshl_add_u64 v[132:133], v[132:133], 0, s[94:95]
	s_lshl_b64 s[18:19], s[18:19], 17
	global_load_dwordx2 v[148:149], v[134:135], off sc1
	global_load_dwordx2 v[144:145], v[132:133], off sc1
	v_lshl_add_u64 v[132:133], v[130:131], 0, s[18:19]
	v_lshl_add_u64 v[134:135], v[132:133], 0, s[90:91]
	s_or_b32 s18, s50, 7
	global_load_dwordx2 v[146:147], v[134:135], off sc1
	v_lshl_add_u64 v[134:135], v[132:133], 0, s[92:93]
	s_ashr_i32 s19, s18, 31
	global_load_dwordx2 v[142:143], v[134:135], off sc1
	v_lshl_add_u64 v[134:135], v[132:133], 0, s[88:89]
	s_lshl_b64 s[18:19], s[18:19], 17
	global_load_dwordx2 v[140:141], v[134:135], off sc1
	s_waitcnt vmcnt(26)
	v_lshlrev_b32_e32 v212, 16, v158
	v_and_b32_e32 v213, 0xffff0000, v158
	v_lshlrev_b32_e32 v158, 16, v159
	v_and_b32_e32 v159, 0xffff0000, v159
	v_pk_add_f32 v[212:213], v[212:213], 0 op_sel_hi:[1,0]
	v_pk_add_f32 v[158:159], v[158:159], 0 op_sel_hi:[1,0]
	s_waitcnt vmcnt(25)
	v_lshlrev_b32_e32 v214, 16, v160
	v_and_b32_e32 v215, 0xffff0000, v160
	v_lshlrev_b32_e32 v160, 16, v161
	v_and_b32_e32 v161, 0xffff0000, v161
	v_pk_add_f32 v[214:215], v[214:215], 0 op_sel_hi:[1,0]
	v_pk_add_f32 v[160:161], v[160:161], 0 op_sel_hi:[1,0]
	s_waitcnt vmcnt(24)
	v_lshlrev_b32_e32 v216, 16, v168
	s_waitcnt vmcnt(22)
	v_lshlrev_b32_e32 v220, 16, v172
	v_and_b32_e32 v221, 0xffff0000, v172
	v_lshlrev_b32_e32 v172, 16, v173
	v_and_b32_e32 v173, 0xffff0000, v173
	v_and_b32_e32 v217, 0xffff0000, v168
	v_lshlrev_b32_e32 v168, 16, v169
	v_and_b32_e32 v169, 0xffff0000, v169
	v_pk_add_f32 v[158:159], v[158:159], v[172:173]
	v_pk_add_f32 v[172:173], v[212:213], v[220:221]
	s_waitcnt vmcnt(21)
	v_lshlrev_b32_e32 v212, 16, v174
	v_and_b32_e32 v213, 0xffff0000, v174
	v_lshlrev_b32_e32 v174, 16, v175
	v_and_b32_e32 v175, 0xffff0000, v175
	v_pk_add_f32 v[216:217], v[216:217], 0 op_sel_hi:[1,0]
	v_pk_add_f32 v[168:169], v[168:169], 0 op_sel_hi:[1,0]
	v_lshlrev_b32_e32 v218, 16, v170
	v_and_b32_e32 v219, 0xffff0000, v170
	v_lshlrev_b32_e32 v170, 16, v171
	v_and_b32_e32 v171, 0xffff0000, v171
	v_pk_add_f32 v[160:161], v[160:161], v[174:175]
	v_pk_add_f32 v[174:175], v[214:215], v[212:213]
	s_waitcnt vmcnt(20)
	v_lshlrev_b32_e32 v212, 16, v176
	v_and_b32_e32 v213, 0xffff0000, v176
	v_lshlrev_b32_e32 v176, 16, v177
	v_and_b32_e32 v177, 0xffff0000, v177
	v_pk_add_f32 v[218:219], v[218:219], 0 op_sel_hi:[1,0]
	v_pk_add_f32 v[170:171], v[170:171], 0 op_sel_hi:[1,0]
	v_pk_add_f32 v[168:169], v[168:169], v[176:177]
	v_pk_add_f32 v[176:177], v[216:217], v[212:213]
	s_waitcnt vmcnt(19)
	v_lshlrev_b32_e32 v212, 16, v178
	v_and_b32_e32 v213, 0xffff0000, v178
	v_lshlrev_b32_e32 v178, 16, v179
	v_and_b32_e32 v179, 0xffff0000, v179
	v_pk_add_f32 v[170:171], v[170:171], v[178:179]
	v_pk_add_f32 v[178:179], v[218:219], v[212:213]
	s_waitcnt vmcnt(18)
	v_lshlrev_b32_e32 v212, 16, v180
	v_and_b32_e32 v213, 0xffff0000, v180
	v_lshlrev_b32_e32 v180, 16, v181
	v_and_b32_e32 v181, 0xffff0000, v181
	v_pk_add_f32 v[158:159], v[158:159], v[180:181]
	s_waitcnt vmcnt(17)
	v_lshlrev_b32_e32 v180, 16, v182
	v_and_b32_e32 v181, 0xffff0000, v182
	v_lshlrev_b32_e32 v182, 16, v183
	v_and_b32_e32 v183, 0xffff0000, v183
	v_pk_add_f32 v[174:175], v[174:175], v[180:181]
	s_waitcnt vmcnt(16)
	v_lshlrev_b32_e32 v180, 16, v194
	v_and_b32_e32 v181, 0xffff0000, v194
	v_pk_add_f32 v[160:161], v[160:161], v[182:183]
	v_lshlrev_b32_e32 v182, 16, v195
	v_and_b32_e32 v183, 0xffff0000, v195
	v_pk_add_f32 v[176:177], v[176:177], v[180:181]
	s_waitcnt vmcnt(15)
	v_lshlrev_b32_e32 v180, 16, v196
	v_and_b32_e32 v181, 0xffff0000, v196
	v_lshl_add_u64 v[132:133], v[132:133], 0, s[94:95]
	v_lshl_add_u64 v[130:131], v[130:131], 0, s[18:19]
	v_pk_add_f32 v[172:173], v[172:173], v[212:213]
	v_pk_add_f32 v[168:169], v[168:169], v[182:183]
	v_lshlrev_b32_e32 v182, 16, v197
	v_and_b32_e32 v183, 0xffff0000, v197
	v_pk_add_f32 v[178:179], v[178:179], v[180:181]
	s_waitcnt vmcnt(14)
	v_lshlrev_b32_e32 v180, 16, v198
	v_and_b32_e32 v181, 0xffff0000, v198
	global_load_dwordx2 v[136:137], v[132:133], off sc1
	v_lshl_add_u64 v[132:133], v[130:131], 0, s[90:91]
	v_pk_add_f32 v[170:171], v[170:171], v[182:183]
	v_lshlrev_b32_e32 v182, 16, v199
	v_and_b32_e32 v183, 0xffff0000, v199
	v_pk_add_f32 v[172:173], v[172:173], v[180:181]
	s_waitcnt vmcnt(14)
	v_lshlrev_b32_e32 v180, 16, v200
	v_and_b32_e32 v181, 0xffff0000, v200
	global_load_dwordx2 v[138:139], v[132:133], off sc1
	v_lshl_add_u64 v[132:133], v[130:131], 0, s[92:93]
	v_pk_add_f32 v[158:159], v[158:159], v[182:183]
	v_lshlrev_b32_e32 v182, 16, v201
	v_and_b32_e32 v183, 0xffff0000, v201
	v_pk_add_f32 v[174:175], v[174:175], v[180:181]
	s_waitcnt vmcnt(14)
	v_lshlrev_b32_e32 v180, 16, v202
	v_and_b32_e32 v181, 0xffff0000, v202
	global_load_dwordx2 v[134:135], v[132:133], off sc1
	v_lshl_add_u64 v[132:133], v[130:131], 0, s[88:89]
	v_pk_add_f32 v[160:161], v[160:161], v[182:183]
	v_lshlrev_b32_e32 v182, 16, v203
	v_and_b32_e32 v183, 0xffff0000, v203
	v_pk_add_f32 v[176:177], v[176:177], v[180:181]
	s_waitcnt vmcnt(14)
	v_lshlrev_b32_e32 v180, 16, v204
	v_and_b32_e32 v181, 0xffff0000, v204
	global_load_dwordx2 v[132:133], v[132:133], off sc1
	v_lshl_add_u64 v[130:131], v[130:131], 0, s[94:95]
	v_pk_add_f32 v[168:169], v[168:169], v[182:183]
	v_lshlrev_b32_e32 v182, 16, v205
	v_and_b32_e32 v183, 0xffff0000, v205
	v_pk_add_f32 v[178:179], v[178:179], v[180:181]
	s_waitcnt vmcnt(14)
	v_lshlrev_b32_e32 v180, 16, v207
	v_and_b32_e32 v181, 0xffff0000, v207
	global_load_dwordx2 v[130:131], v[130:131], off sc1
	v_pk_add_f32 v[182:183], v[170:171], v[182:183]
	v_lshlrev_b32_e32 v170, 16, v206
	v_and_b32_e32 v171, 0xffff0000, v206
	v_pk_add_f32 v[180:181], v[158:159], v[180:181]
	s_waitcnt vmcnt(14)
	v_lshlrev_b32_e32 v158, 16, v208
	v_and_b32_e32 v159, 0xffff0000, v208
	s_lshl_b32 s3, s12, 8
	s_lshl_b32 s1, s1, 7
	v_pk_add_f32 v[172:173], v[172:173], v[170:171]
	v_lshlrev_b32_e32 v170, 16, v209
	v_and_b32_e32 v171, 0xffff0000, v209
	v_pk_add_f32 v[174:175], v[174:175], v[158:159]
	s_waitcnt vmcnt(13)
	v_lshlrev_b32_e32 v158, 16, v210
	v_and_b32_e32 v159, 0xffff0000, v210
	s_add_i32 s1, s1, s3
	v_pk_add_f32 v[194:195], v[160:161], v[170:171]
	v_lshlrev_b32_e32 v160, 16, v211
	v_and_b32_e32 v161, 0xffff0000, v211
	v_pk_add_f32 v[176:177], v[176:177], v[158:159]
	v_add_u32_e32 v158, s1, v185
	v_pk_add_f32 v[196:197], v[168:169], v[160:161]
	v_lshl_or_b32 v160, s0, 4, v158
	v_lshl_or_b32 v158, s14, 7, v189
	v_ashrrev_i32_e32 v161, 31, v160
	v_lshlrev_b64 v[168:169], 10, v[160:161]
	v_ashrrev_i32_e32 v159, 31, v158
	v_readlane_b32 s0, v255, 0
	s_waitcnt vmcnt(12)
	v_lshlrev_b32_e32 v198, 16, v164
	v_lshl_add_u64 v[200:201], v[168:169], 0, v[158:159]
	v_readlane_b32 s1, v255, 1
	v_and_b32_e32 v199, 0xffff0000, v164
	v_pk_add_f32 v[178:179], v[178:179], v[198:199]
	v_lshl_add_u64 v[168:169], v[200:201], 1, s[0:1]
	v_lshl_add_u64 v[198:199], s[42:43], 0, v[200:201]
	global_load_dwordx4 v[168:171], v[168:169], off
	v_lshlrev_b32_e32 v164, 16, v165
	global_load_dwordx2 v[198:199], v[198:199], off
	v_and_b32_e32 v165, 0xffff0000, v165
	v_pk_add_f32 v[164:165], v[182:183], v[164:165]
	s_waitcnt vmcnt(13)
	v_lshlrev_b32_e32 v182, 16, v166
	v_and_b32_e32 v183, 0xffff0000, v166
	v_lshlrev_b32_e32 v166, 16, v167
	v_and_b32_e32 v167, 0xffff0000, v167
	v_pk_add_f32 v[166:167], v[180:181], v[166:167]
	s_waitcnt vmcnt(12)
	v_lshlrev_b32_e32 v180, 16, v162
	v_and_b32_e32 v181, 0xffff0000, v162
	v_pk_add_f32 v[174:175], v[174:175], v[180:181]
	s_waitcnt vmcnt(11)
	v_lshlrev_b32_e32 v180, 16, v148
	v_and_b32_e32 v181, 0xffff0000, v148
	v_pk_add_f32 v[176:177], v[176:177], v[180:181]
	s_waitcnt vmcnt(10)
	v_lshlrev_b32_e32 v180, 16, v144
	v_and_b32_e32 v181, 0xffff0000, v144
	v_lshlrev_b32_e32 v144, 16, v145
	v_and_b32_e32 v145, 0xffff0000, v145
	v_lshlrev_b32_e32 v162, 16, v163
	v_and_b32_e32 v163, 0xffff0000, v163
	v_pk_add_f32 v[144:145], v[164:165], v[144:145]
	v_pk_add_f32 v[164:165], v[178:179], v[180:181]
	s_waitcnt vmcnt(9)
	v_lshlrev_b32_e32 v178, 16, v146
	v_and_b32_e32 v179, 0xffff0000, v146
	v_lshlrev_b32_e32 v146, 16, v147
	v_and_b32_e32 v147, 0xffff0000, v147
	v_pk_add_f32 v[162:163], v[194:195], v[162:163]
	v_lshlrev_b32_e32 v148, 16, v149
	v_and_b32_e32 v149, 0xffff0000, v149
	v_pk_add_f32 v[146:147], v[166:167], v[146:147]
	s_waitcnt vmcnt(8)
	v_lshlrev_b32_e32 v166, 16, v142
	v_and_b32_e32 v167, 0xffff0000, v142
	v_lshlrev_b32_e32 v142, 16, v143
	v_and_b32_e32 v143, 0xffff0000, v143
	v_pk_add_f32 v[148:149], v[196:197], v[148:149]
	v_pk_add_f32 v[142:143], v[162:163], v[142:143]
	s_waitcnt vmcnt(7)
	v_lshlrev_b32_e32 v162, 16, v140
	v_and_b32_e32 v163, 0xffff0000, v140
	v_lshlrev_b32_e32 v140, 16, v141
	v_and_b32_e32 v141, 0xffff0000, v141
	v_pk_add_f32 v[140:141], v[148:149], v[140:141]
	s_waitcnt vmcnt(6)
	v_lshlrev_b32_e32 v148, 16, v136
	v_and_b32_e32 v149, 0xffff0000, v136
	v_lshlrev_b32_e32 v136, 16, v137
	v_and_b32_e32 v137, 0xffff0000, v137
	v_pk_add_f32 v[136:137], v[144:145], v[136:137]
	s_waitcnt vmcnt(5)
	v_lshlrev_b32_e32 v144, 16, v138
	v_and_b32_e32 v145, 0xffff0000, v138
	v_lshlrev_b32_e32 v138, 16, v139
	v_and_b32_e32 v139, 0xffff0000, v139
	v_pk_add_f32 v[166:167], v[174:175], v[166:167]
	v_pk_add_f32 v[138:139], v[146:147], v[138:139]
	s_waitcnt vmcnt(4)
	v_lshlrev_b32_e32 v146, 16, v134
	v_and_b32_e32 v147, 0xffff0000, v134
	v_lshlrev_b32_e32 v134, 16, v135
	v_and_b32_e32 v135, 0xffff0000, v135
	v_pk_add_f32 v[162:163], v[176:177], v[162:163]
	v_pk_add_f32 v[134:135], v[142:143], v[134:135]
	v_pk_add_f32 v[142:143], v[166:167], v[146:147]
	s_waitcnt vmcnt(3)
	v_lshlrev_b32_e32 v146, 16, v132
	v_and_b32_e32 v147, 0xffff0000, v132
	v_lshlrev_b32_e32 v132, 16, v133
	v_and_b32_e32 v133, 0xffff0000, v133
	v_pk_add_f32 v[148:149], v[164:165], v[148:149]
	v_pk_add_f32 v[132:133], v[140:141], v[132:133]
	v_pk_add_f32 v[140:141], v[162:163], v[146:147]
	s_waitcnt vmcnt(2)
	v_lshlrev_b32_e32 v146, 16, v130
	v_and_b32_e32 v147, 0xffff0000, v130
	v_lshlrev_b32_e32 v130, 16, v131
	v_and_b32_e32 v131, 0xffff0000, v131
	v_pk_add_f32 v[130:131], v[136:137], v[130:131]
	v_pk_add_f32 v[136:137], v[148:149], v[146:147]
	v_mul_f32_e32 v140, 0xbfb8aa3b, v140
	v_exp_f32_e32 v140, v140
	v_mul_f32_e32 v136, 0xbfb8aa3b, v136
	v_exp_f32_e32 v136, v136
	v_mul_f32_e32 v141, 0xbfb8aa3b, v141
	v_exp_f32_e32 v141, v141
	v_mul_f32_e32 v137, 0xbfb8aa3b, v137
	v_exp_f32_e32 v137, v137
	v_mul_f32_e32 v132, 0xbfb8aa3b, v132
	v_exp_f32_e32 v132, v132
	v_mul_f32_e32 v130, 0xbfb8aa3b, v130
	v_add_f32_e32 v140, 1.0, v140
	v_pk_add_f32 v[172:173], v[172:173], v[182:183]
	v_exp_f32_e32 v130, v130
	v_mul_f32_e32 v133, 0xbfb8aa3b, v133
	v_rcp_f32_e32 v140, v140
	v_add_f32_e32 v136, 1.0, v136
	v_pk_add_f32 v[172:173], v[172:173], v[178:179]
	s_waitcnt vmcnt(0)
	v_cvt_f32_ubyte0_e32 v166, v198
	v_exp_f32_e32 v133, v133
	v_mul_f32_e32 v131, 0xbfb8aa3b, v131
	v_rcp_f32_e32 v136, v136
	v_add_f32_e32 v141, 1.0, v141
	v_pk_add_f32 v[144:145], v[172:173], v[144:145]
	v_lshlrev_b32_e32 v162, 16, v170
	v_and_b32_e32 v163, 0xffff0000, v170
	v_mul_f32_e32 v166, 0x3b808081, v166
	v_cvt_f32_ubyte0_e32 v170, v199
	v_exp_f32_e32 v131, v131
	v_rcp_f32_e32 v141, v141
	v_add_f32_e32 v137, 1.0, v137
	v_lshlrev_b32_e32 v146, 16, v168
	v_cvt_f32_ubyte1_e32 v167, v198
	v_mul_f32_e32 v170, 0x3b808081, v170
	v_rcp_f32_e32 v137, v137
	v_add_f32_e32 v132, 1.0, v132
	v_mul_f32_e32 v144, v166, v144
	v_lshlrev_b32_e32 v164, 16, v171
	v_and_b32_e32 v165, 0xffff0000, v171
	v_mul_f32_e32 v167, 0x3b808081, v167
	v_cvt_f32_ubyte1_e32 v171, v199
	v_rcp_f32_e32 v132, v132
	v_add_f32_e32 v130, 1.0, v130
	v_fmac_f32_e32 v146, v144, v140
	v_mul_f32_e32 v140, v170, v142
	v_and_b32_e32 v147, 0xffff0000, v168
	v_cvt_f32_ubyte2_e32 v168, v198
	v_mul_f32_e32 v171, 0x3b808081, v171
	v_rcp_f32_e32 v130, v130
	v_add_f32_e32 v133, 1.0, v133
	v_fmac_f32_e32 v162, v140, v136
	v_mul_f32_e32 v136, v145, v167
	v_mul_f32_e32 v168, 0x3b808081, v168
	v_cvt_f32_ubyte2_e32 v172, v199
	v_rcp_f32_e32 v133, v133
	v_add_f32_e32 v131, 1.0, v131
	v_fmac_f32_e32 v147, v136, v141
	v_mul_f32_e32 v136, v171, v143
	v_lshlrev_b32_e32 v148, 16, v169
	v_and_b32_e32 v149, 0xffff0000, v169
	v_cvt_f32_ubyte3_e32 v169, v198
	v_mul_f32_e32 v172, 0x3b808081, v172
	v_rcp_f32_e32 v131, v131
	v_fmac_f32_e32 v163, v136, v137
	v_mul_f32_e32 v136, v138, v168
	v_mul_f32_e32 v169, 0x3b808081, v169
	v_cvt_f32_ubyte3_e32 v173, v199
	v_fmac_f32_e32 v148, v136, v132
	v_mul_f32_e32 v132, v172, v134
	v_mul_f32_e32 v173, 0x3b808081, v173
	v_fmac_f32_e32 v164, v132, v130
	v_mul_f32_e32 v130, v169, v139
	v_fmac_f32_e32 v149, v130, v133
	v_mul_f32_e32 v130, v173, v135
	v_fmac_f32_e32 v165, v130, v131
	v_cvt_pk_bf16_f32 v130, v146, v147
	v_cvt_pk_bf16_f32 v131, v148, v149
	v_cvt_pk_bf16_f32 v132, v162, v163
	v_cvt_pk_bf16_f32 v133, v164, v165
	s_branch .LBB0_1354

.LBB0_1469:
	s_cmp_gt_i32 s53, -1
	s_cbranch_scc0 .LBB0_1481
	s_lshl_b32 s6, s96, 3
	s_add_i32 s18, s6, s53
	s_ashr_i32 s19, s18, 31
	s_lshl_b64 s[18:19], s[18:19], 17
	v_mov_b32_e32 v130, v0
	s_add_u32 s18, s68, s18
	s_addc_u32 s19, s69, s19
	v_ashrrev_i32_e32 v131, 31, v130
	v_lshl_add_u64 v[130:131], v[130:131], 4, s[18:19]
	v_cvt_pk_bf16_f32 v132, v126, v127
	v_cvt_pk_bf16_f32 v133, v128, v129
	v_cvt_pk_bf16_f32 v134, v122, v123
	v_cvt_pk_bf16_f32 v135, v124, v125
	global_store_dwordx4 v[130:131], v[132:135], off sc1
	s_nop 1
	v_cvt_pk_bf16_f32 v132, v110, v111
	v_cvt_pk_bf16_f32 v133, v112, v113
	v_cvt_pk_bf16_f32 v134, v106, v107
	v_cvt_pk_bf16_f32 v135, v108, v109
	s_mov_b64 s[98:99], 0x2000
	v_lshl_add_u64 v[136:137], v[130:131], 0, s[98:99]
	global_store_dwordx4 v[136:137], v[132:135], off sc1
	s_nop 1
	v_cvt_pk_bf16_f32 v132, v94, v95
	v_cvt_pk_bf16_f32 v133, v96, v97
	v_cvt_pk_bf16_f32 v134, v90, v91
	v_cvt_pk_bf16_f32 v135, v92, v93
	s_mov_b64 s[98:99], 0x4000
	v_lshl_add_u64 v[136:137], v[130:131], 0, s[98:99]
	global_store_dwordx4 v[136:137], v[132:135], off sc1
	s_nop 1
	v_cvt_pk_bf16_f32 v132, v78, v79
	v_cvt_pk_bf16_f32 v133, v80, v81
	v_cvt_pk_bf16_f32 v134, v74, v75
	v_cvt_pk_bf16_f32 v135, v76, v77
	s_mov_b64 s[98:99], 0x6000
	v_lshl_add_u64 v[136:137], v[130:131], 0, s[98:99]
	global_store_dwordx4 v[136:137], v[132:135], off sc1
	s_nop 1
	v_cvt_pk_bf16_f32 v132, v118, v119
	v_cvt_pk_bf16_f32 v133, v120, v121
	v_cvt_pk_bf16_f32 v134, v114, v115
	v_cvt_pk_bf16_f32 v135, v116, v117
	s_mov_b64 s[98:99], 0x8000
	v_lshl_add_u64 v[136:137], v[130:131], 0, s[98:99]
	global_store_dwordx4 v[136:137], v[132:135], off sc1
	s_nop 1
	v_cvt_pk_bf16_f32 v132, v102, v103
	v_cvt_pk_bf16_f32 v133, v104, v105
	v_cvt_pk_bf16_f32 v134, v98, v99
	v_cvt_pk_bf16_f32 v135, v100, v101
	s_mov_b64 s[98:99], 0xa000
	v_lshl_add_u64 v[136:137], v[130:131], 0, s[98:99]
	global_store_dwordx4 v[136:137], v[132:135], off sc1
	s_nop 1
	v_cvt_pk_bf16_f32 v132, v86, v87
	v_cvt_pk_bf16_f32 v133, v88, v89
	v_cvt_pk_bf16_f32 v134, v82, v83
	v_cvt_pk_bf16_f32 v135, v84, v85
	s_mov_b64 s[98:99], 0xc000
	v_lshl_add_u64 v[136:137], v[130:131], 0, s[98:99]
	global_store_dwordx4 v[136:137], v[132:135], off sc1
	s_nop 1
	v_cvt_pk_bf16_f32 v132, v70, v71
	v_cvt_pk_bf16_f32 v133, v72, v73
	v_cvt_pk_bf16_f32 v134, v66, v67
	v_cvt_pk_bf16_f32 v135, v68, v69
	s_mov_b64 s[98:99], 0xe000
	v_lshl_add_u64 v[136:137], v[130:131], 0, s[98:99]
	global_store_dwordx4 v[136:137], v[132:135], off sc1
	s_nop 1
	v_cvt_pk_bf16_f32 v132, v62, v63
	v_cvt_pk_bf16_f32 v133, v64, v65
	v_cvt_pk_bf16_f32 v134, v58, v59
	v_cvt_pk_bf16_f32 v135, v60, v61
	s_mov_b64 s[98:99], 0x10000
	v_lshl_add_u64 v[136:137], v[130:131], 0, s[98:99]
	global_store_dwordx4 v[136:137], v[132:135], off sc1
	s_nop 1
	v_cvt_pk_bf16_f32 v132, v46, v47
	v_cvt_pk_bf16_f32 v133, v48, v49
	v_cvt_pk_bf16_f32 v134, v42, v43
	v_cvt_pk_bf16_f32 v135, v44, v45
	s_mov_b64 s[98:99], 0x12000
	v_lshl_add_u64 v[136:137], v[130:131], 0, s[98:99]
	global_store_dwordx4 v[136:137], v[132:135], off sc1
	s_nop 1
	v_cvt_pk_bf16_f32 v132, v30, v31
	v_cvt_pk_bf16_f32 v133, v32, v33
	v_cvt_pk_bf16_f32 v134, v26, v27
	v_cvt_pk_bf16_f32 v135, v28, v29
	s_mov_b64 s[98:99], 0x14000
	v_lshl_add_u64 v[136:137], v[130:131], 0, s[98:99]
	global_store_dwordx4 v[136:137], v[132:135], off sc1
	s_nop 1
	v_cvt_pk_bf16_f32 v132, v14, v15
	v_cvt_pk_bf16_f32 v133, v16, v17
	v_cvt_pk_bf16_f32 v134, v10, v11
	v_cvt_pk_bf16_f32 v135, v12, v13
	s_mov_b64 s[98:99], 0x16000
	v_lshl_add_u64 v[136:137], v[130:131], 0, s[98:99]
	global_store_dwordx4 v[136:137], v[132:135], off sc1
	s_nop 1
	v_cvt_pk_bf16_f32 v132, v54, v55
	v_cvt_pk_bf16_f32 v133, v56, v57
	v_cvt_pk_bf16_f32 v134, v50, v51
	v_cvt_pk_bf16_f32 v135, v52, v53
	s_mov_b64 s[98:99], 0x18000
	v_lshl_add_u64 v[136:137], v[130:131], 0, s[98:99]
	global_store_dwordx4 v[136:137], v[132:135], off sc1
	s_nop 1
	v_cvt_pk_bf16_f32 v132, v38, v39
	v_cvt_pk_bf16_f32 v133, v40, v41
	v_cvt_pk_bf16_f32 v134, v34, v35
	v_cvt_pk_bf16_f32 v135, v36, v37
	s_mov_b64 s[98:99], 0x1a000
	v_lshl_add_u64 v[136:137], v[130:131], 0, s[98:99]
	global_store_dwordx4 v[136:137], v[132:135], off sc1
	s_nop 1
	v_cvt_pk_bf16_f32 v132, v22, v23
	v_cvt_pk_bf16_f32 v133, v24, v25
	v_cvt_pk_bf16_f32 v134, v18, v19
	v_cvt_pk_bf16_f32 v135, v20, v21
	s_mov_b64 s[98:99], 0x1c000
	v_lshl_add_u64 v[136:137], v[130:131], 0, s[98:99]
	global_store_dwordx4 v[136:137], v[132:135], off sc1
	s_nop 1
	v_cvt_pk_bf16_f32 v132, v6, v7
	v_cvt_pk_bf16_f32 v133, v8, v9
	v_cvt_pk_bf16_f32 v134, v2, v3
	v_cvt_pk_bf16_f32 v135, v4, v5
	s_mov_b64 s[98:99], 0x1e000
	v_lshl_add_u64 v[136:137], v[130:131], 0, s[98:99]
	global_store_dwordx4 v[136:137], v[132:135], off sc1
	s_nop 1
	s_waitcnt vmcnt(0)
	s_waitcnt vmcnt(0)
	s_barrier
	s_and_saveexec_b64 s[50:51], s[0:1]
	s_cbranch_execz .LBB0_1484
	s_lshl_b32 s18, s96, 6
	s_mov_b64 s[88:89], exec
	s_ashr_i32 s19, s18, 31
	s_lshl_b64 s[18:19], s[18:19], 2
	v_readlane_b32 s7, v255, 19
	v_mbcnt_lo_u32_b32 v130, s88, 0
	s_add_u32 s86, s7, s18
	v_readlane_b32 s7, v255, 21
	v_mbcnt_hi_u32_b32 v130, s89, v130
	s_addc_u32 s87, s7, s19
	v_cmp_eq_u32_e32 vcc, 0, v130
	s_and_saveexec_b64 s[90:91], vcc
	s_cbranch_execz .LBB0_1473
	s_bcnt1_i32_b64 s7, s[88:89]
	v_mov_b32_e32 v130, s7
	global_atomic_add v191, v130, s[86:87]

.LBB0_1484:
	s_or_b64 exec, exec, s[50:51]
	s_lshr_b32 s33, s53, 2
	s_and_b32 s73, s53, 3
	v_mov_b32_e32 v130, v0
	s_lshl_b32 s7, s33, 4
	s_lshl_b32 s11, s73, 1
	s_barrier
	s_or_b32 s18, s7, s11
	v_ashrrev_i32_e32 v131, 31, v130
	s_ashr_i32 s7, s6, 31
	v_lshl_add_u64 v[130:131], v[130:131], 4, s[68:69]
	s_or_b32 s44, s18, 8
	s_lshl_b64 s[20:21], s[6:7], 17
	s_mov_b32 s19, s45
	s_lshl_b64 s[50:51], s[44:45], 12
	v_lshl_add_u64 v[132:133], v[130:131], 0, s[20:21]
	s_lshl_b64 s[86:87], s[18:19], 12
	s_or_b32 s44, s18, 1
	v_lshl_add_u64 v[134:135], v[132:133], 0, s[86:87]
	s_add_u32 s88, s86, 8
	s_addc_u32 s89, s87, 0
	s_or_b32 s44, s18, 9
	s_or_b32 s18, s6, 1
	global_load_dwordx2 v[154:155], v[134:135], off sc1
	v_lshl_add_u64 v[134:135], v[132:133], 0, s[88:89]
	s_add_u32 s90, s50, 8
	s_addc_u32 s91, s51, 0
	s_ashr_i32 s19, s18, 31
	global_load_dwordx2 v[156:157], v[134:135], off sc1
	v_lshl_add_u64 v[134:135], v[132:133], 0, s[50:51]
	v_lshl_add_u64 v[132:133], v[132:133], 0, s[90:91]
	s_lshl_b64 s[18:19], s[18:19], 17
	global_load_dwordx2 v[158:159], v[134:135], off sc1
	global_load_dwordx2 v[160:161], v[132:133], off sc1
	v_lshl_add_u64 v[132:133], v[130:131], 0, s[18:19]
	v_lshl_add_u64 v[134:135], v[132:133], 0, s[86:87]
	s_or_b32 s18, s6, 2
	global_load_dwordx2 v[162:163], v[134:135], off sc1
	v_lshl_add_u64 v[134:135], v[132:133], 0, s[88:89]
	s_ashr_i32 s19, s18, 31
	global_load_dwordx2 v[164:165], v[134:135], off sc1
	v_lshl_add_u64 v[134:135], v[132:133], 0, s[50:51]
	v_lshl_add_u64 v[132:133], v[132:133], 0, s[90:91]
	s_lshl_b64 s[18:19], s[18:19], 17
	global_load_dwordx2 v[166:167], v[134:135], off sc1
	global_load_dwordx2 v[168:169], v[132:133], off sc1
	v_lshl_add_u64 v[132:133], v[130:131], 0, s[18:19]
	v_lshl_add_u64 v[134:135], v[132:133], 0, s[86:87]
	s_or_b32 s18, s6, 3
	global_load_dwordx2 v[170:171], v[134:135], off sc1
	v_lshl_add_u64 v[134:135], v[132:133], 0, s[88:89]
	s_ashr_i32 s19, s18, 31
	global_load_dwordx2 v[172:173], v[134:135], off sc1
	v_lshl_add_u64 v[134:135], v[132:133], 0, s[50:51]
	v_lshl_add_u64 v[132:133], v[132:133], 0, s[90:91]
	s_lshl_b64 s[18:19], s[18:19], 17
	global_load_dwordx2 v[174:175], v[134:135], off sc1
	global_load_dwordx2 v[176:177], v[132:133], off sc1
	v_lshl_add_u64 v[132:133], v[130:131], 0, s[18:19]
	v_lshl_add_u64 v[134:135], v[132:133], 0, s[86:87]
	s_or_b32 s18, s6, 4
	global_load_dwordx2 v[178:179], v[134:135], off sc1
	v_lshl_add_u64 v[134:135], v[132:133], 0, s[88:89]
	s_ashr_i32 s19, s18, 31
	global_load_dwordx2 v[180:181], v[134:135], off sc1
	v_lshl_add_u64 v[134:135], v[132:133], 0, s[50:51]
	v_lshl_add_u64 v[132:133], v[132:133], 0, s[90:91]
	s_lshl_b64 s[18:19], s[18:19], 17
	global_load_dwordx2 v[182:183], v[134:135], off sc1
	global_load_dwordx2 v[184:185], v[132:133], off sc1
	v_lshl_add_u64 v[132:133], v[130:131], 0, s[18:19]
	v_lshl_add_u64 v[134:135], v[132:133], 0, s[86:87]
	global_load_dwordx2 v[196:197], v[134:135], off sc1
	v_lshl_add_u64 v[134:135], v[132:133], 0, s[88:89]
	global_load_dwordx2 v[198:199], v[134:135], off sc1
	v_lshl_add_u64 v[134:135], v[132:133], 0, s[50:51]
	global_load_dwordx2 v[200:201], v[134:135], off sc1
	s_or_b32 s18, s6, 5
	s_ashr_i32 s19, s18, 31
	v_lshl_add_u64 v[132:133], v[132:133], 0, s[90:91]
	s_lshl_b64 s[18:19], s[18:19], 17
	global_load_dwordx2 v[202:203], v[132:133], off sc1
	v_lshl_add_u64 v[132:133], v[130:131], 0, s[18:19]
	v_lshl_add_u64 v[134:135], v[132:133], 0, s[86:87]
	global_load_dwordx2 v[152:153], v[134:135], off sc1
	v_lshl_add_u64 v[134:135], v[132:133], 0, s[88:89]
	global_load_dwordx2 v[150:151], v[134:135], off sc1
	v_lshl_add_u64 v[134:135], v[132:133], 0, s[50:51]
	global_load_dwordx2 v[148:149], v[134:135], off sc1
	v_lshl_add_u64 v[132:133], v[132:133], 0, s[90:91]
	global_load_dwordx2 v[144:145], v[132:133], off sc1
	s_or_b32 s18, s6, 6
	s_ashr_i32 s19, s18, 31
	s_lshl_b64 s[18:19], s[18:19], 17
	v_lshl_add_u64 v[132:133], v[130:131], 0, s[18:19]
	v_lshl_add_u64 v[134:135], v[132:133], 0, s[86:87]
	s_or_b32 s6, s6, 7
	global_load_dwordx2 v[146:147], v[134:135], off sc1
	v_lshl_add_u64 v[134:135], v[132:133], 0, s[88:89]
	s_ashr_i32 s7, s6, 31
	global_load_dwordx2 v[142:143], v[134:135], off sc1
	v_lshl_add_u64 v[134:135], v[132:133], 0, s[50:51]
	s_lshl_b64 s[6:7], s[6:7], 17
	global_load_dwordx2 v[140:141], v[134:135], off sc1
	s_waitcnt vmcnt(26)
	v_lshlrev_b32_e32 v204, 16, v154
	v_and_b32_e32 v205, 0xffff0000, v154
	v_lshlrev_b32_e32 v154, 16, v155
	v_and_b32_e32 v155, 0xffff0000, v155
	v_pk_add_f32 v[154:155], v[154:155], 0 op_sel_hi:[1,0]
	s_waitcnt vmcnt(25)
	v_lshlrev_b32_e32 v206, 16, v156
	v_and_b32_e32 v207, 0xffff0000, v156
	v_lshlrev_b32_e32 v156, 16, v157
	v_and_b32_e32 v157, 0xffff0000, v157
	v_pk_add_f32 v[156:157], v[156:157], 0 op_sel_hi:[1,0]
	s_waitcnt vmcnt(24)
	v_lshlrev_b32_e32 v208, 16, v158
	v_and_b32_e32 v209, 0xffff0000, v158
	v_lshlrev_b32_e32 v158, 16, v159
	s_waitcnt vmcnt(22)
	v_lshlrev_b32_e32 v222, 16, v162
	v_and_b32_e32 v223, 0xffff0000, v162
	v_lshlrev_b32_e32 v162, 16, v163
	v_and_b32_e32 v163, 0xffff0000, v163
	v_and_b32_e32 v159, 0xffff0000, v159
	v_pk_add_f32 v[154:155], v[154:155], v[162:163]
	s_waitcnt vmcnt(21)
	v_lshlrev_b32_e32 v162, 16, v164
	v_and_b32_e32 v163, 0xffff0000, v164
	v_lshlrev_b32_e32 v164, 16, v165
	v_and_b32_e32 v165, 0xffff0000, v165
	v_pk_add_f32 v[158:159], v[158:159], 0 op_sel_hi:[1,0]
	v_lshlrev_b32_e32 v210, 16, v160
	v_and_b32_e32 v211, 0xffff0000, v160
	v_lshlrev_b32_e32 v160, 16, v161
	v_and_b32_e32 v161, 0xffff0000, v161
	v_pk_add_f32 v[156:157], v[156:157], v[164:165]
	s_waitcnt vmcnt(20)
	v_lshlrev_b32_e32 v164, 16, v166
	v_and_b32_e32 v165, 0xffff0000, v166
	v_lshlrev_b32_e32 v166, 16, v167
	v_and_b32_e32 v167, 0xffff0000, v167
	v_pk_add_f32 v[160:161], v[160:161], 0 op_sel_hi:[1,0]
	v_pk_add_f32 v[158:159], v[158:159], v[166:167]
	s_waitcnt vmcnt(19)
	v_lshlrev_b32_e32 v166, 16, v168
	v_and_b32_e32 v167, 0xffff0000, v168
	v_lshlrev_b32_e32 v168, 16, v169
	v_and_b32_e32 v169, 0xffff0000, v169
	v_pk_add_f32 v[160:161], v[160:161], v[168:169]
	s_waitcnt vmcnt(18)
	v_lshlrev_b32_e32 v168, 16, v170
	v_and_b32_e32 v169, 0xffff0000, v170
	v_lshlrev_b32_e32 v170, 16, v171
	v_and_b32_e32 v171, 0xffff0000, v171
	v_pk_add_f32 v[154:155], v[154:155], v[170:171]
	s_waitcnt vmcnt(17)
	v_lshlrev_b32_e32 v170, 16, v172
	v_and_b32_e32 v171, 0xffff0000, v172
	v_lshlrev_b32_e32 v172, 16, v173
	v_and_b32_e32 v173, 0xffff0000, v173
	v_pk_add_f32 v[206:207], v[206:207], 0 op_sel_hi:[1,0]
	v_pk_add_f32 v[156:157], v[156:157], v[172:173]
	s_waitcnt vmcnt(16)
	v_lshlrev_b32_e32 v172, 16, v175
	v_and_b32_e32 v173, 0xffff0000, v175
	v_pk_add_f32 v[208:209], v[208:209], 0 op_sel_hi:[1,0]
	v_pk_add_f32 v[162:163], v[206:207], v[162:163]
	v_pk_add_f32 v[158:159], v[158:159], v[172:173]
	s_waitcnt vmcnt(15)
	v_lshlrev_b32_e32 v172, 16, v177
	v_and_b32_e32 v173, 0xffff0000, v177
	v_pk_add_f32 v[204:205], v[204:205], 0 op_sel_hi:[1,0]
	v_pk_add_f32 v[210:211], v[210:211], 0 op_sel_hi:[1,0]
	v_pk_add_f32 v[164:165], v[208:209], v[164:165]
	v_pk_add_f32 v[162:163], v[162:163], v[170:171]
	v_lshlrev_b32_e32 v170, 16, v174
	v_and_b32_e32 v171, 0xffff0000, v174
	v_pk_add_f32 v[160:161], v[160:161], v[172:173]
	s_waitcnt vmcnt(14)
	v_lshlrev_b32_e32 v172, 16, v179
	v_and_b32_e32 v173, 0xffff0000, v179
	v_pk_add_f32 v[204:205], v[204:205], v[222:223]
	v_pk_add_f32 v[166:167], v[210:211], v[166:167]
	v_pk_add_f32 v[164:165], v[164:165], v[170:171]
	v_lshlrev_b32_e32 v170, 16, v176
	v_and_b32_e32 v171, 0xffff0000, v176
	v_pk_add_f32 v[154:155], v[154:155], v[172:173]
	s_waitcnt vmcnt(13)
	v_lshlrev_b32_e32 v172, 16, v181
	v_and_b32_e32 v173, 0xffff0000, v181
	v_pk_add_f32 v[168:169], v[204:205], v[168:169]
	v_pk_add_f32 v[166:167], v[166:167], v[170:171]
	v_lshlrev_b32_e32 v170, 16, v178
	v_and_b32_e32 v171, 0xffff0000, v178
	v_pk_add_f32 v[156:157], v[156:157], v[172:173]
	s_waitcnt vmcnt(12)
	v_lshlrev_b32_e32 v172, 16, v183
	v_and_b32_e32 v173, 0xffff0000, v183
	v_pk_add_f32 v[168:169], v[168:169], v[170:171]
	v_lshlrev_b32_e32 v170, 16, v180
	v_and_b32_e32 v171, 0xffff0000, v180
	v_pk_add_f32 v[158:159], v[158:159], v[172:173]
	s_waitcnt vmcnt(11)
	v_lshlrev_b32_e32 v172, 16, v185
	v_and_b32_e32 v173, 0xffff0000, v185
	v_lshl_add_u64 v[132:133], v[132:133], 0, s[90:91]
	v_lshl_add_u64 v[130:131], v[130:131], 0, s[6:7]
	v_pk_add_f32 v[162:163], v[162:163], v[170:171]
	v_lshlrev_b32_e32 v170, 16, v182
	v_and_b32_e32 v171, 0xffff0000, v182
	v_pk_add_f32 v[160:161], v[160:161], v[172:173]
	s_waitcnt vmcnt(10)
	v_lshlrev_b32_e32 v172, 16, v197
	v_and_b32_e32 v173, 0xffff0000, v197
	global_load_dwordx2 v[136:137], v[132:133], off sc1
	v_lshl_add_u64 v[132:133], v[130:131], 0, s[86:87]
	v_pk_add_f32 v[164:165], v[164:165], v[170:171]
	v_lshlrev_b32_e32 v170, 16, v184
	v_and_b32_e32 v171, 0xffff0000, v184
	v_pk_add_f32 v[172:173], v[154:155], v[172:173]
	s_waitcnt vmcnt(10)
	v_lshlrev_b32_e32 v154, 16, v198
	v_and_b32_e32 v155, 0xffff0000, v198
	global_load_dwordx2 v[138:139], v[132:133], off sc1
	v_lshl_add_u64 v[132:133], v[130:131], 0, s[88:89]
	v_pk_add_f32 v[166:167], v[166:167], v[170:171]
	v_lshlrev_b32_e32 v170, 16, v196
	v_and_b32_e32 v171, 0xffff0000, v196
	v_pk_add_f32 v[162:163], v[162:163], v[154:155]
	s_waitcnt vmcnt(10)
	v_lshlrev_b32_e32 v154, 16, v200
	v_and_b32_e32 v155, 0xffff0000, v200
	s_lshl_b32 s11, s24, 8
	v_lshl_add_u32 v182, s33, 7, v214
	global_load_dwordx2 v[134:135], v[132:133], off sc1
	v_lshl_add_u64 v[132:133], v[130:131], 0, s[50:51]
	v_pk_add_f32 v[168:169], v[168:169], v[170:171]
	v_lshlrev_b32_e32 v170, 16, v199
	v_and_b32_e32 v171, 0xffff0000, v199
	v_pk_add_f32 v[164:165], v[164:165], v[154:155]
	s_lshl_b32 s6, s73, 4
	v_add_u32_e32 v154, s11, v182
	global_load_dwordx2 v[132:133], v[132:133], off sc1
	v_lshl_add_u64 v[130:131], v[130:131], 0, s[90:91]
	v_pk_add_f32 v[170:171], v[156:157], v[170:171]
	v_lshlrev_b32_e32 v156, 16, v201
	v_and_b32_e32 v157, 0xffff0000, v201
	v_or_b32_e32 v154, s6, v154
	global_load_dwordx2 v[130:131], v[130:131], off sc1
	v_pk_add_f32 v[158:159], v[158:159], v[156:157]
	v_lshl_or_b32 v156, s10, 8, v217
	v_ashrrev_i32_e32 v155, 31, v154
	v_readlane_b32 s18, v254, 62
	v_ashrrev_i32_e32 v157, 31, v156
	v_lshlrev_b64 v[154:155], 11, v[154:155]
	v_readlane_b32 s19, v254, 63
	v_lshlrev_b64 v[178:179], 1, v[156:157]
	s_waitcnt vmcnt(12)
	v_lshlrev_b32_e32 v174, 16, v202
	v_lshl_add_u64 v[154:155], s[18:19], 0, v[154:155]
	v_lshl_add_u64 v[180:181], v[154:155], 0, v[178:179]
	global_load_dwordx4 v[154:157], v[180:181], off
	v_and_b32_e32 v175, 0xffff0000, v202
	v_pk_add_f32 v[166:167], v[166:167], v[174:175]
	s_waitcnt vmcnt(12)
	v_lshlrev_b32_e32 v174, 16, v152
	v_and_b32_e32 v175, 0xffff0000, v152
	v_lshlrev_b32_e32 v152, 16, v153
	v_and_b32_e32 v153, 0xffff0000, v153
	v_pk_add_f32 v[152:153], v[172:173], v[152:153]
	s_waitcnt vmcnt(11)
	v_lshlrev_b32_e32 v172, 16, v150
	v_and_b32_e32 v173, 0xffff0000, v150
	v_lshlrev_b32_e32 v150, 16, v151
	v_and_b32_e32 v151, 0xffff0000, v151
	v_pk_add_f32 v[170:171], v[170:171], v[150:151]
	s_waitcnt vmcnt(10)
	v_lshlrev_b32_e32 v150, 16, v148
	v_and_b32_e32 v151, 0xffff0000, v148
	v_lshlrev_b32_e32 v148, 16, v149
	v_and_b32_e32 v149, 0xffff0000, v149
	v_pk_add_f32 v[158:159], v[158:159], v[148:149]
	s_waitcnt vmcnt(9)
	v_lshlrev_b32_e32 v148, 16, v144
	v_and_b32_e32 v149, 0xffff0000, v144
	v_pk_add_f32 v[164:165], v[164:165], v[150:151]
	v_pk_add_f32 v[166:167], v[166:167], v[148:149]
	global_load_dwordx4 v[148:151], v[180:181], off offset:256
	v_lshlrev_b32_e32 v176, 16, v203
	v_and_b32_e32 v177, 0xffff0000, v203
	v_pk_add_f32 v[160:161], v[160:161], v[176:177]
	v_lshlrev_b32_e32 v144, 16, v145
	v_and_b32_e32 v145, 0xffff0000, v145
	v_pk_add_f32 v[168:169], v[168:169], v[174:175]
	v_pk_add_f32 v[144:145], v[160:161], v[144:145]
	s_waitcnt vmcnt(9)
	v_lshlrev_b32_e32 v160, 16, v146
	v_and_b32_e32 v161, 0xffff0000, v146
	v_lshlrev_b32_e32 v146, 16, v147
	v_and_b32_e32 v147, 0xffff0000, v147
	v_pk_add_f32 v[162:163], v[162:163], v[172:173]
	v_pk_add_f32 v[146:147], v[152:153], v[146:147]
	v_pk_add_f32 v[152:153], v[168:169], v[160:161]
	s_waitcnt vmcnt(8)
	v_lshlrev_b32_e32 v160, 16, v142
	v_and_b32_e32 v161, 0xffff0000, v142
	v_pk_add_f32 v[160:161], v[162:163], v[160:161]
	s_waitcnt vmcnt(7)
	v_lshlrev_b32_e32 v162, 16, v140
	v_and_b32_e32 v163, 0xffff0000, v140
	v_lshlrev_b32_e32 v140, 16, v141
	v_and_b32_e32 v141, 0xffff0000, v141
	v_pk_add_f32 v[140:141], v[158:159], v[140:141]
	v_pk_add_f32 v[158:159], v[164:165], v[162:163]
	s_waitcnt vmcnt(6)
	v_lshlrev_b32_e32 v162, 16, v136
	v_and_b32_e32 v163, 0xffff0000, v136
	v_lshlrev_b32_e32 v136, 16, v137
	v_and_b32_e32 v137, 0xffff0000, v137
	v_lshlrev_b32_e32 v142, 16, v143
	v_and_b32_e32 v143, 0xffff0000, v143
	v_pk_add_f32 v[136:137], v[144:145], v[136:137]
	v_pk_add_f32 v[144:145], v[166:167], v[162:163]
	s_waitcnt vmcnt(5)
	v_lshlrev_b32_e32 v162, 16, v138
	v_and_b32_e32 v163, 0xffff0000, v138
	v_lshlrev_b32_e32 v138, 16, v139
	v_and_b32_e32 v139, 0xffff0000, v139
	v_pk_add_f32 v[142:143], v[170:171], v[142:143]
	v_pk_add_f32 v[138:139], v[146:147], v[138:139]
	s_waitcnt vmcnt(4)
	v_lshlrev_b32_e32 v146, 16, v134
	v_and_b32_e32 v147, 0xffff0000, v134
	v_lshlrev_b32_e32 v134, 16, v135
	v_and_b32_e32 v135, 0xffff0000, v135
	v_pk_add_f32 v[134:135], v[142:143], v[134:135]
	s_waitcnt vmcnt(3)
	v_lshlrev_b32_e32 v142, 16, v132
	v_and_b32_e32 v143, 0xffff0000, v132
	v_lshlrev_b32_e32 v132, 16, v133
	v_and_b32_e32 v133, 0xffff0000, v133
	v_pk_add_f32 v[140:141], v[140:141], v[132:133]
	s_waitcnt vmcnt(2)
	v_lshlrev_b32_e32 v132, 16, v130
	v_and_b32_e32 v133, 0xffff0000, v130
	v_lshlrev_b32_e32 v130, 16, v131
	v_and_b32_e32 v131, 0xffff0000, v131
	v_pk_add_f32 v[136:137], v[136:137], v[130:131]
	v_or_b32_e32 v130, s6, v182
	v_pk_add_f32 v[144:145], v[144:145], v[132:133]
	v_add_u32_e32 v132, s11, v130
	v_ashrrev_i32_e32 v133, 31, v132
	v_pk_add_f32 v[152:153], v[152:153], v[162:163]
	v_pk_add_f32 v[142:143], v[158:159], v[142:143]
	v_lshlrev_b64 v[158:159], 11, v[132:133]
	s_waitcnt vmcnt(1)
	v_lshlrev_b32_e32 v132, 16, v154
	v_and_b32_e32 v133, 0xffff0000, v154
	v_lshlrev_b32_e32 v154, 16, v155
	v_and_b32_e32 v155, 0xffff0000, v155
	v_pk_add_f32 v[146:147], v[160:161], v[146:147]
	v_lshlrev_b32_e32 v160, 16, v156
	v_and_b32_e32 v161, 0xffff0000, v156
	v_lshlrev_b32_e32 v156, 16, v157
	v_and_b32_e32 v157, 0xffff0000, v157
	v_pk_add_f32 v[138:139], v[138:139], v[154:155]
	v_pk_add_f32 v[132:133], v[152:153], v[132:133]
	v_pk_add_f32 v[152:153], v[134:135], v[156:157]
	v_pk_add_f32 v[134:135], v[146:147], v[160:161]
	v_mul_f32_e32 v131, v133, v133
	v_mul_f32_e32 v146, v139, v139
	v_fmac_f32_e32 v131, v132, v132
	v_fmac_f32_e32 v146, v138, v138
	v_add_f32_e32 v131, v131, v146
	v_mul_f32_e32 v146, v135, v135
	v_mul_f32_e32 v147, v153, v153
	v_fmac_f32_e32 v146, v134, v134
	v_fmac_f32_e32 v147, v152, v152
	v_add_f32_e32 v146, v146, v147
	v_add_f32_e32 v131, v131, v146
	v_cvt_pk_bf16_f32 v132, v132, v133
	v_cvt_pk_bf16_f32 v133, v138, v139
	s_waitcnt vmcnt(0)
	v_lshlrev_b32_e32 v138, 16, v148
	v_and_b32_e32 v139, 0xffff0000, v148
	v_lshlrev_b32_e32 v146, 16, v149
	v_and_b32_e32 v147, 0xffff0000, v149
	v_lshlrev_b32_e32 v148, 16, v150
	v_and_b32_e32 v149, 0xffff0000, v150
	v_lshlrev_b32_e32 v150, 16, v151
	v_and_b32_e32 v151, 0xffff0000, v151
	v_pk_add_f32 v[140:141], v[140:141], v[146:147]
	v_pk_add_f32 v[138:139], v[142:143], v[138:139]
	v_pk_add_f32 v[142:143], v[136:137], v[150:151]
	v_pk_add_f32 v[136:137], v[144:145], v[148:149]
	v_mul_f32_e32 v144, v139, v139
	v_mul_f32_e32 v145, v141, v141
	v_fmac_f32_e32 v144, v138, v138
	v_fmac_f32_e32 v145, v140, v140
	v_add_f32_e32 v144, v144, v145
	v_mul_f32_e32 v145, v137, v137
	v_mul_f32_e32 v146, v143, v143
	v_fmac_f32_e32 v145, v136, v136
	v_fmac_f32_e32 v146, v142, v142
	v_add_f32_e32 v145, v145, v146
	v_add_f32_e32 v144, v144, v145
	v_and_b32_e32 v145, 64, v221
	v_add_f32_e32 v131, v131, v144
	v_xor_b32_e32 v144, 16, v221
	v_add_u32_e32 v146, 64, v145
	v_cmp_lt_i32_e32 vcc, v144, v146
	v_cvt_pk_bf16_f32 v134, v134, v135
	v_cvt_pk_bf16_f32 v135, v152, v153
	s_nop 1
	v_cndmask_b32_e32 v144, v221, v144, vcc
	v_lshlrev_b32_e32 v144, 2, v144
	ds_bpermute_b32 v147, v144, v131
	v_lshl_add_u64 v[144:145], s[42:43], 0, v[158:159]
	v_lshl_add_u64 v[144:145], v[144:145], 0, v[178:179]
	global_store_dwordx4 v[144:145], v[132:135], off
	s_waitcnt lgkmcnt(0)
	v_add_f32_e32 v131, v131, v147
	v_xor_b32_e32 v132, 32, v221
	v_cmp_lt_i32_e32 vcc, v132, v146
	v_cvt_pk_bf16_f32 v134, v138, v139
	v_cvt_pk_bf16_f32 v135, v140, v141
	v_cvt_pk_bf16_f32 v136, v136, v137
	v_cvt_pk_bf16_f32 v137, v142, v143
	global_store_dwordx4 v[144:145], v[134:137], off offset:256
	s_nop 0
	v_cndmask_b32_e32 v132, v221, v132, vcc
	v_lshlrev_b32_e32 v132, 2, v132
	ds_bpermute_b32 v132, v132, v131
	s_and_saveexec_b64 s[6:7], s[4:5]
	s_cbranch_execz .LBB0_1486
	v_lshl_add_u32 v130, v130, 4, s15
	s_waitcnt lgkmcnt(0)
	v_add_f32_e32 v131, v131, v132
	ds_write_b32 v130, v131

.LBB0_2132:
	s_cmp_gt_i32 s73, -1
	s_mov_b64 s[58:59], -1
	s_cbranch_scc0 .LBB0_2144
	s_lshl_b32 s58, s2, 3
	s_add_i32 s36, s58, s73
	s_ashr_i32 s37, s36, 31
	s_lshl_b64 s[36:37], s[36:37], 17
	v_readlane_b32 s60, v254, 62
	v_mov_b32_e32 v130, v0
	v_readlane_b32 s61, v254, 63
	s_add_u32 s36, s60, s36
	s_addc_u32 s37, s61, s37
	v_ashrrev_i32_e32 v131, 31, v130
	v_lshl_add_u64 v[130:131], v[130:131], 4, s[36:37]
	v_cvt_pk_bf16_f32 v132, v126, v127
	v_cvt_pk_bf16_f32 v133, v128, v129
	v_cvt_pk_bf16_f32 v134, v122, v123
	v_cvt_pk_bf16_f32 v135, v124, v125
	global_store_dwordx4 v[130:131], v[132:135], off sc1
	s_nop 1
	v_cvt_pk_bf16_f32 v132, v110, v111
	v_cvt_pk_bf16_f32 v133, v112, v113
	v_cvt_pk_bf16_f32 v134, v106, v107
	v_cvt_pk_bf16_f32 v135, v108, v109
	s_mov_b64 s[98:99], 0x2000
	v_lshl_add_u64 v[136:137], v[130:131], 0, s[98:99]
	global_store_dwordx4 v[136:137], v[132:135], off sc1
	s_nop 1
	v_cvt_pk_bf16_f32 v132, v94, v95
	v_cvt_pk_bf16_f32 v133, v96, v97
	v_cvt_pk_bf16_f32 v134, v90, v91
	v_cvt_pk_bf16_f32 v135, v92, v93
	s_mov_b64 s[98:99], 0x4000
	v_lshl_add_u64 v[136:137], v[130:131], 0, s[98:99]
	global_store_dwordx4 v[136:137], v[132:135], off sc1
	s_nop 1
	v_cvt_pk_bf16_f32 v132, v78, v79
	v_cvt_pk_bf16_f32 v133, v80, v81
	v_cvt_pk_bf16_f32 v134, v74, v75
	v_cvt_pk_bf16_f32 v135, v76, v77
	s_mov_b64 s[98:99], 0x6000
	v_lshl_add_u64 v[136:137], v[130:131], 0, s[98:99]
	global_store_dwordx4 v[136:137], v[132:135], off sc1
	s_nop 1
	v_cvt_pk_bf16_f32 v132, v118, v119
	v_cvt_pk_bf16_f32 v133, v120, v121
	v_cvt_pk_bf16_f32 v134, v114, v115
	v_cvt_pk_bf16_f32 v135, v116, v117
	s_mov_b64 s[98:99], 0x8000
	v_lshl_add_u64 v[136:137], v[130:131], 0, s[98:99]
	global_store_dwordx4 v[136:137], v[132:135], off sc1
	s_nop 1
	v_cvt_pk_bf16_f32 v132, v102, v103
	v_cvt_pk_bf16_f32 v133, v104, v105
	v_cvt_pk_bf16_f32 v134, v98, v99
	v_cvt_pk_bf16_f32 v135, v100, v101
	s_mov_b64 s[98:99], 0xa000
	v_lshl_add_u64 v[136:137], v[130:131], 0, s[98:99]
	global_store_dwordx4 v[136:137], v[132:135], off sc1
	s_nop 1
	v_cvt_pk_bf16_f32 v132, v86, v87
	v_cvt_pk_bf16_f32 v133, v88, v89
	v_cvt_pk_bf16_f32 v134, v82, v83
	v_cvt_pk_bf16_f32 v135, v84, v85
	s_mov_b64 s[98:99], 0xc000
	v_lshl_add_u64 v[136:137], v[130:131], 0, s[98:99]
	global_store_dwordx4 v[136:137], v[132:135], off sc1
	s_nop 1
	v_cvt_pk_bf16_f32 v132, v70, v71
	v_cvt_pk_bf16_f32 v133, v72, v73
	v_cvt_pk_bf16_f32 v134, v62, v63
	v_cvt_pk_bf16_f32 v135, v64, v65
	s_mov_b64 s[98:99], 0xe000
	v_lshl_add_u64 v[136:137], v[130:131], 0, s[98:99]
	global_store_dwordx4 v[136:137], v[132:135], off sc1
	s_nop 1
	v_cvt_pk_bf16_f32 v132, v66, v67
	v_cvt_pk_bf16_f32 v133, v68, v69
	v_cvt_pk_bf16_f32 v134, v58, v59
	v_cvt_pk_bf16_f32 v135, v60, v61
	s_mov_b64 s[98:99], 0x10000
	v_lshl_add_u64 v[136:137], v[130:131], 0, s[98:99]
	global_store_dwordx4 v[136:137], v[132:135], off sc1
	s_nop 1
	v_cvt_pk_bf16_f32 v132, v46, v47
	v_cvt_pk_bf16_f32 v133, v48, v49
	v_cvt_pk_bf16_f32 v134, v42, v43
	v_cvt_pk_bf16_f32 v135, v44, v45
	s_mov_b64 s[98:99], 0x12000
	v_lshl_add_u64 v[136:137], v[130:131], 0, s[98:99]
	global_store_dwordx4 v[136:137], v[132:135], off sc1
	s_nop 1
	v_cvt_pk_bf16_f32 v132, v30, v31
	v_cvt_pk_bf16_f32 v133, v32, v33
	v_cvt_pk_bf16_f32 v134, v26, v27
	v_cvt_pk_bf16_f32 v135, v28, v29
	s_mov_b64 s[98:99], 0x14000
	v_lshl_add_u64 v[136:137], v[130:131], 0, s[98:99]
	global_store_dwordx4 v[136:137], v[132:135], off sc1
	s_nop 1
	v_cvt_pk_bf16_f32 v132, v14, v15
	v_cvt_pk_bf16_f32 v133, v16, v17
	v_cvt_pk_bf16_f32 v134, v10, v11
	v_cvt_pk_bf16_f32 v135, v12, v13
	s_mov_b64 s[98:99], 0x16000
	v_lshl_add_u64 v[136:137], v[130:131], 0, s[98:99]
	global_store_dwordx4 v[136:137], v[132:135], off sc1
	s_nop 1
	v_cvt_pk_bf16_f32 v132, v54, v55
	v_cvt_pk_bf16_f32 v133, v56, v57
	v_cvt_pk_bf16_f32 v134, v50, v51
	v_cvt_pk_bf16_f32 v135, v52, v53
	s_mov_b64 s[98:99], 0x18000
	v_lshl_add_u64 v[136:137], v[130:131], 0, s[98:99]
	global_store_dwordx4 v[136:137], v[132:135], off sc1
	s_nop 1
	v_cvt_pk_bf16_f32 v132, v38, v39
	v_cvt_pk_bf16_f32 v133, v40, v41
	v_cvt_pk_bf16_f32 v134, v34, v35
	v_cvt_pk_bf16_f32 v135, v36, v37
	s_mov_b64 s[98:99], 0x1a000
	v_lshl_add_u64 v[136:137], v[130:131], 0, s[98:99]
	global_store_dwordx4 v[136:137], v[132:135], off sc1
	s_nop 1
	v_cvt_pk_bf16_f32 v132, v22, v23
	v_cvt_pk_bf16_f32 v133, v24, v25
	v_cvt_pk_bf16_f32 v134, v18, v19
	v_cvt_pk_bf16_f32 v135, v20, v21
	s_mov_b64 s[98:99], 0x1c000
	v_lshl_add_u64 v[136:137], v[130:131], 0, s[98:99]
	global_store_dwordx4 v[136:137], v[132:135], off sc1
	s_nop 1
	v_cvt_pk_bf16_f32 v132, v6, v7
	v_cvt_pk_bf16_f32 v133, v8, v9
	v_cvt_pk_bf16_f32 v134, v2, v3
	v_cvt_pk_bf16_f32 v135, v4, v5
	s_mov_b64 s[98:99], 0x1e000
	v_lshl_add_u64 v[136:137], v[130:131], 0, s[98:99]
	global_store_dwordx4 v[136:137], v[132:135], off sc1
	s_nop 1
	s_waitcnt vmcnt(0)
	s_waitcnt vmcnt(0)
	s_barrier
	s_and_saveexec_b64 s[60:61], s[0:1]
	s_cbranch_execz .LBB0_2145
	s_lshl_b32 s36, s2, 6
	s_mov_b64 s[64:65], exec
	s_ashr_i32 s37, s36, 31
	s_lshl_b64 s[36:37], s[36:37], 2
	v_readlane_b32 s17, v255, 21
	v_mbcnt_lo_u32_b32 v130, s64, 0
	s_add_u32 s62, s17, s36
	v_readlane_b32 s17, v255, 17
	v_mbcnt_hi_u32_b32 v130, s65, v130
	s_addc_u32 s63, s17, s37
	v_cmp_eq_u32_e32 vcc, 0, v130
	s_and_saveexec_b64 s[66:67], vcc
	s_cbranch_execz .LBB0_2136
	s_bcnt1_i32_b64 s17, s[64:65]
	v_mov_b32_e32 v130, s17
	global_atomic_add v197, v130, s[62:63]

.LBB0_2145:
	s_or_b64 exec, exec, s[60:61]
	v_mov_b32_e32 v130, v0
	v_readlane_b32 s36, v254, 62
	s_barrier
	s_lshr_b32 s17, s73, 2
	s_and_b32 vcc_lo, s73, 3
	v_readlane_b32 s37, v254, 63
	v_ashrrev_i32_e32 v131, 31, v130
	s_lshl_b32 s33, s17, 4
	v_lshl_add_u64 v[130:131], v[130:131], 4, s[36:37]
	s_lshl_b32 s36, vcc_lo, 1
	s_or_b32 s36, s33, s36
	s_ashr_i32 s59, s58, 31
	s_or_b32 s40, s36, 8
	s_lshl_b64 s[62:63], s[58:59], 17
	s_mov_b32 s37, s41
	s_lshl_b64 s[60:61], s[40:41], 12
	v_lshl_add_u64 v[132:133], v[130:131], 0, s[62:63]
	s_lshl_b64 s[62:63], s[36:37], 12
	s_or_b32 s40, s36, 1
	v_lshl_add_u64 v[134:135], v[132:133], 0, s[62:63]
	s_add_u32 s64, s62, 8
	s_addc_u32 s65, s63, 0
	s_or_b32 s40, s36, 9
	s_or_b32 s36, s58, 1
	global_load_dwordx2 v[154:155], v[134:135], off sc1
	v_lshl_add_u64 v[134:135], v[132:133], 0, s[64:65]
	s_add_u32 s66, s60, 8
	s_addc_u32 s67, s61, 0
	s_ashr_i32 s37, s36, 31
	global_load_dwordx2 v[156:157], v[134:135], off sc1
	v_lshl_add_u64 v[134:135], v[132:133], 0, s[60:61]
	v_lshl_add_u64 v[132:133], v[132:133], 0, s[66:67]
	s_lshl_b64 s[36:37], s[36:37], 17
	global_load_dwordx2 v[158:159], v[134:135], off sc1
	global_load_dwordx2 v[160:161], v[132:133], off sc1
	v_lshl_add_u64 v[132:133], v[130:131], 0, s[36:37]
	v_lshl_add_u64 v[134:135], v[132:133], 0, s[62:63]
	s_or_b32 s36, s58, 2
	global_load_dwordx2 v[162:163], v[134:135], off sc1
	v_lshl_add_u64 v[134:135], v[132:133], 0, s[64:65]
	s_ashr_i32 s37, s36, 31
	global_load_dwordx2 v[164:165], v[134:135], off sc1
	v_lshl_add_u64 v[134:135], v[132:133], 0, s[60:61]
	v_lshl_add_u64 v[132:133], v[132:133], 0, s[66:67]
	s_lshl_b64 s[36:37], s[36:37], 17
	global_load_dwordx2 v[166:167], v[134:135], off sc1
	global_load_dwordx2 v[168:169], v[132:133], off sc1
	v_lshl_add_u64 v[132:133], v[130:131], 0, s[36:37]
	v_lshl_add_u64 v[134:135], v[132:133], 0, s[62:63]
	s_or_b32 s36, s58, 3
	global_load_dwordx2 v[170:171], v[134:135], off sc1
	v_lshl_add_u64 v[134:135], v[132:133], 0, s[64:65]
	s_ashr_i32 s37, s36, 31
	global_load_dwordx2 v[172:173], v[134:135], off sc1
	v_lshl_add_u64 v[134:135], v[132:133], 0, s[60:61]
	v_lshl_add_u64 v[132:133], v[132:133], 0, s[66:67]
	s_lshl_b64 s[36:37], s[36:37], 17
	global_load_dwordx2 v[174:175], v[134:135], off sc1
	global_load_dwordx2 v[176:177], v[132:133], off sc1
	v_lshl_add_u64 v[132:133], v[130:131], 0, s[36:37]
	v_lshl_add_u64 v[134:135], v[132:133], 0, s[62:63]
	s_or_b32 s36, s58, 4
	global_load_dwordx2 v[178:179], v[134:135], off sc1
	v_lshl_add_u64 v[134:135], v[132:133], 0, s[64:65]
	s_ashr_i32 s37, s36, 31
	global_load_dwordx2 v[180:181], v[134:135], off sc1
	v_lshl_add_u64 v[134:135], v[132:133], 0, s[60:61]
	v_lshl_add_u64 v[132:133], v[132:133], 0, s[66:67]
	s_lshl_b64 s[36:37], s[36:37], 17
	global_load_dwordx2 v[182:183], v[134:135], off sc1
	global_load_dwordx2 v[184:185], v[132:133], off sc1
	v_lshl_add_u64 v[132:133], v[130:131], 0, s[36:37]
	v_lshl_add_u64 v[134:135], v[132:133], 0, s[62:63]
	global_load_dwordx2 v[186:187], v[134:135], off sc1
	v_lshl_add_u64 v[134:135], v[132:133], 0, s[64:65]
	global_load_dwordx2 v[188:189], v[134:135], off sc1
	v_lshl_add_u64 v[134:135], v[132:133], 0, s[60:61]
	global_load_dwordx2 v[190:191], v[134:135], off sc1
	v_lshl_add_u64 v[132:133], v[132:133], 0, s[66:67]
	global_load_dwordx2 v[192:193], v[132:133], off sc1
	s_or_b32 s36, s58, 5
	s_ashr_i32 s37, s36, 31
	s_lshl_b64 s[36:37], s[36:37], 17
	v_lshl_add_u64 v[132:133], v[130:131], 0, s[36:37]
	v_lshl_add_u64 v[134:135], v[132:133], 0, s[62:63]
	global_load_dwordx2 v[152:153], v[134:135], off sc1
	v_lshl_add_u64 v[134:135], v[132:133], 0, s[64:65]
	global_load_dwordx2 v[150:151], v[134:135], off sc1
	v_lshl_add_u64 v[134:135], v[132:133], 0, s[60:61]
	global_load_dwordx2 v[148:149], v[134:135], off sc1
	s_or_b32 s36, s58, 6
	s_ashr_i32 s37, s36, 31
	v_lshl_add_u64 v[132:133], v[132:133], 0, s[66:67]
	s_lshl_b64 s[36:37], s[36:37], 17
	global_load_dwordx2 v[144:145], v[132:133], off sc1
	v_lshl_add_u64 v[132:133], v[130:131], 0, s[36:37]
	v_lshl_add_u64 v[134:135], v[132:133], 0, s[62:63]
	s_or_b32 s36, s58, 7
	global_load_dwordx2 v[146:147], v[134:135], off sc1
	v_lshl_add_u64 v[134:135], v[132:133], 0, s[64:65]
	s_ashr_i32 s37, s36, 31
	global_load_dwordx2 v[142:143], v[134:135], off sc1
	v_lshl_add_u64 v[134:135], v[132:133], 0, s[60:61]
	s_lshl_b64 s[36:37], s[36:37], 17
	global_load_dwordx2 v[140:141], v[134:135], off sc1
	v_lshl_add_u64 v[132:133], v[132:133], 0, s[66:67]
	v_lshl_add_u64 v[130:131], v[130:131], 0, s[36:37]
	global_load_dwordx2 v[136:137], v[132:133], off sc1
	v_lshl_add_u64 v[132:133], v[130:131], 0, s[62:63]
	global_load_dwordx2 v[138:139], v[132:133], off sc1
	v_lshl_add_u64 v[132:133], v[130:131], 0, s[64:65]
	global_load_dwordx2 v[134:135], v[132:133], off sc1
	s_waitcnt vmcnt(29)
	v_lshlrev_b32_e32 v200, 16, v154
	v_and_b32_e32 v201, 0xffff0000, v154
	v_lshlrev_b32_e32 v154, 16, v155
	v_and_b32_e32 v155, 0xffff0000, v155
	v_pk_add_f32 v[154:155], v[154:155], 0 op_sel_hi:[1,0]
	s_waitcnt vmcnt(28)
	v_lshlrev_b32_e32 v202, 16, v156
	v_and_b32_e32 v203, 0xffff0000, v156
	v_lshlrev_b32_e32 v156, 16, v157
	v_and_b32_e32 v157, 0xffff0000, v157
	s_waitcnt vmcnt(25)
	v_lshlrev_b32_e32 v208, 16, v162
	v_and_b32_e32 v209, 0xffff0000, v162
	v_lshlrev_b32_e32 v162, 16, v163
	v_and_b32_e32 v163, 0xffff0000, v163
	v_pk_add_f32 v[156:157], v[156:157], 0 op_sel_hi:[1,0]
	v_lshlrev_b32_e32 v204, 16, v158
	v_and_b32_e32 v205, 0xffff0000, v158
	v_lshlrev_b32_e32 v158, 16, v159
	v_and_b32_e32 v159, 0xffff0000, v159
	v_pk_add_f32 v[154:155], v[154:155], v[162:163]
	s_waitcnt vmcnt(24)
	v_lshlrev_b32_e32 v162, 16, v164
	v_and_b32_e32 v163, 0xffff0000, v164
	v_lshlrev_b32_e32 v164, 16, v165
	v_and_b32_e32 v165, 0xffff0000, v165
	v_pk_add_f32 v[158:159], v[158:159], 0 op_sel_hi:[1,0]
	v_lshlrev_b32_e32 v206, 16, v160
	v_and_b32_e32 v207, 0xffff0000, v160
	v_lshlrev_b32_e32 v160, 16, v161
	v_and_b32_e32 v161, 0xffff0000, v161
	v_pk_add_f32 v[156:157], v[156:157], v[164:165]
	s_waitcnt vmcnt(23)
	v_lshlrev_b32_e32 v164, 16, v166
	v_and_b32_e32 v165, 0xffff0000, v166
	v_lshlrev_b32_e32 v166, 16, v167
	v_and_b32_e32 v167, 0xffff0000, v167
	v_pk_add_f32 v[160:161], v[160:161], 0 op_sel_hi:[1,0]
	v_pk_add_f32 v[158:159], v[158:159], v[166:167]
	s_waitcnt vmcnt(22)
	v_lshlrev_b32_e32 v166, 16, v168
	v_and_b32_e32 v167, 0xffff0000, v168
	v_lshlrev_b32_e32 v168, 16, v169
	v_and_b32_e32 v169, 0xffff0000, v169
	v_pk_add_f32 v[160:161], v[160:161], v[168:169]
	s_waitcnt vmcnt(21)
	v_lshlrev_b32_e32 v168, 16, v170
	v_and_b32_e32 v169, 0xffff0000, v170
	v_lshlrev_b32_e32 v170, 16, v171
	v_and_b32_e32 v171, 0xffff0000, v171
	v_pk_add_f32 v[154:155], v[154:155], v[170:171]
	s_waitcnt vmcnt(20)
	v_lshlrev_b32_e32 v170, 16, v172
	v_and_b32_e32 v171, 0xffff0000, v172
	v_lshlrev_b32_e32 v172, 16, v173
	v_and_b32_e32 v173, 0xffff0000, v173
	v_pk_add_f32 v[156:157], v[156:157], v[172:173]
	s_waitcnt vmcnt(19)
	v_lshlrev_b32_e32 v172, 16, v175
	v_and_b32_e32 v173, 0xffff0000, v175
	v_pk_add_f32 v[202:203], v[202:203], 0 op_sel_hi:[1,0]
	v_pk_add_f32 v[158:159], v[158:159], v[172:173]
	s_waitcnt vmcnt(18)
	v_lshlrev_b32_e32 v172, 16, v177
	v_and_b32_e32 v173, 0xffff0000, v177
	v_pk_add_f32 v[204:205], v[204:205], 0 op_sel_hi:[1,0]
	v_pk_add_f32 v[162:163], v[202:203], v[162:163]
	v_pk_add_f32 v[160:161], v[160:161], v[172:173]
	s_waitcnt vmcnt(17)
	v_lshlrev_b32_e32 v172, 16, v179
	v_and_b32_e32 v173, 0xffff0000, v179
	v_pk_add_f32 v[200:201], v[200:201], 0 op_sel_hi:[1,0]
	v_pk_add_f32 v[206:207], v[206:207], 0 op_sel_hi:[1,0]
	v_pk_add_f32 v[164:165], v[204:205], v[164:165]
	v_pk_add_f32 v[162:163], v[162:163], v[170:171]
	v_lshlrev_b32_e32 v170, 16, v174
	v_and_b32_e32 v171, 0xffff0000, v174
	v_pk_add_f32 v[154:155], v[154:155], v[172:173]
	s_waitcnt vmcnt(16)
	v_lshlrev_b32_e32 v172, 16, v181
	v_and_b32_e32 v173, 0xffff0000, v181
	v_pk_add_f32 v[200:201], v[200:201], v[208:209]
	v_pk_add_f32 v[166:167], v[206:207], v[166:167]
	v_pk_add_f32 v[164:165], v[164:165], v[170:171]
	v_lshlrev_b32_e32 v170, 16, v176
	v_and_b32_e32 v171, 0xffff0000, v176
	v_pk_add_f32 v[156:157], v[156:157], v[172:173]
	s_waitcnt vmcnt(15)
	v_lshlrev_b32_e32 v172, 16, v183
	v_and_b32_e32 v173, 0xffff0000, v183
	v_pk_add_f32 v[168:169], v[200:201], v[168:169]
	v_pk_add_f32 v[166:167], v[166:167], v[170:171]
	v_lshlrev_b32_e32 v170, 16, v178
	v_and_b32_e32 v171, 0xffff0000, v178
	v_pk_add_f32 v[158:159], v[158:159], v[172:173]
	s_waitcnt vmcnt(14)
	v_lshlrev_b32_e32 v172, 16, v185
	v_and_b32_e32 v173, 0xffff0000, v185
	v_pk_add_f32 v[168:169], v[168:169], v[170:171]
	v_lshlrev_b32_e32 v170, 16, v180
	v_and_b32_e32 v171, 0xffff0000, v180
	v_pk_add_f32 v[160:161], v[160:161], v[172:173]
	s_waitcnt vmcnt(13)
	v_lshlrev_b32_e32 v172, 16, v187
	v_and_b32_e32 v173, 0xffff0000, v187
	v_pk_add_f32 v[162:163], v[162:163], v[170:171]
	v_lshlrev_b32_e32 v170, 16, v182
	v_and_b32_e32 v171, 0xffff0000, v182
	v_pk_add_f32 v[172:173], v[154:155], v[172:173]
	s_waitcnt vmcnt(12)
	v_lshlrev_b32_e32 v154, 16, v188
	v_and_b32_e32 v155, 0xffff0000, v188
	v_pk_add_f32 v[164:165], v[164:165], v[170:171]
	v_pk_add_f32 v[174:175], v[162:163], v[154:155]
	s_waitcnt vmcnt(11)
	v_lshlrev_b32_e32 v154, 16, v190
	v_and_b32_e32 v155, 0xffff0000, v190
	v_pk_add_f32 v[164:165], v[164:165], v[154:155]
	s_waitcnt vmcnt(10)
	v_lshlrev_b32_e32 v154, 16, v193
	v_and_b32_e32 v155, 0xffff0000, v193
	s_lshl_b32 s33, s72, 8
	v_lshl_add_u32 v162, s17, 7, v217
	v_pk_add_f32 v[160:161], v[160:161], v[154:155]
	s_lshl_b32 s36, vcc_lo, 4
	v_add_u32_e32 v154, s33, v162
	v_or_b32_e32 v154, s36, v154
	v_lshlrev_b32_e32 v170, 16, v184
	v_and_b32_e32 v171, 0xffff0000, v184
	v_ashrrev_i32_e32 v155, 31, v154
	v_lshl_add_u64 v[132:133], v[130:131], 0, s[60:61]
	v_pk_add_f32 v[166:167], v[166:167], v[170:171]
	v_lshlrev_b32_e32 v170, 16, v186
	v_and_b32_e32 v171, 0xffff0000, v186
	v_lshl_or_b32 v200, s16, 8, v222
	v_lshlrev_b64 v[154:155], 11, v[154:155]
	global_load_dwordx2 v[132:133], v[132:133], off sc1
	v_lshl_add_u64 v[130:131], v[130:131], 0, s[66:67]
	v_pk_add_f32 v[168:169], v[168:169], v[170:171]
	v_lshlrev_b32_e32 v170, 16, v189
	v_and_b32_e32 v171, 0xffff0000, v189
	v_ashrrev_i32_e32 v201, 31, v200
	v_lshl_add_u64 v[154:155], s[42:43], 0, v[154:155]
	global_load_dwordx2 v[130:131], v[130:131], off sc1
	v_pk_add_f32 v[170:171], v[156:157], v[170:171]
	v_lshlrev_b32_e32 v156, 16, v191
	v_and_b32_e32 v157, 0xffff0000, v191
	v_lshl_add_u64 v[178:179], v[200:201], 1, v[154:155]
	v_pk_add_f32 v[158:159], v[158:159], v[156:157]
	global_load_dwordx4 v[154:157], v[178:179], off
	v_lshlrev_b32_e32 v176, 16, v192
	v_and_b32_e32 v177, 0xffff0000, v192
	v_pk_add_f32 v[176:177], v[166:167], v[176:177]
	s_waitcnt vmcnt(12)
	v_lshlrev_b32_e32 v166, 16, v152
	v_and_b32_e32 v167, 0xffff0000, v152
	v_lshlrev_b32_e32 v152, 16, v153
	v_and_b32_e32 v153, 0xffff0000, v153
	v_pk_add_f32 v[168:169], v[168:169], v[166:167]
	s_waitcnt vmcnt(11)
	v_lshlrev_b32_e32 v166, 16, v150
	v_and_b32_e32 v167, 0xffff0000, v150
	v_pk_add_f32 v[152:153], v[172:173], v[152:153]
	v_lshlrev_b32_e32 v150, 16, v151
	v_and_b32_e32 v151, 0xffff0000, v151
	v_pk_add_f32 v[172:173], v[174:175], v[166:167]
	s_waitcnt vmcnt(10)
	v_lshlrev_b32_e32 v166, 16, v148
	v_and_b32_e32 v167, 0xffff0000, v148
	v_pk_add_f32 v[150:151], v[170:171], v[150:151]
	v_pk_add_f32 v[170:171], v[164:165], v[166:167]
	global_load_dwordx4 v[164:167], v[178:179], off offset:256
	v_lshlrev_b32_e32 v148, 16, v149
	v_and_b32_e32 v149, 0xffff0000, v149
	v_pk_add_f32 v[148:149], v[158:159], v[148:149]
	s_waitcnt vmcnt(10)
	v_lshlrev_b32_e32 v158, 16, v144
	v_and_b32_e32 v159, 0xffff0000, v144
	v_lshlrev_b32_e32 v144, 16, v145
	v_and_b32_e32 v145, 0xffff0000, v145
	v_pk_add_f32 v[144:145], v[160:161], v[144:145]
	s_waitcnt vmcnt(9)
	v_lshlrev_b32_e32 v160, 16, v146
	v_and_b32_e32 v161, 0xffff0000, v146
	v_lshlrev_b32_e32 v146, 16, v147
	v_and_b32_e32 v147, 0xffff0000, v147
	v_pk_add_f32 v[146:147], v[152:153], v[146:147]
	v_pk_add_f32 v[152:153], v[168:169], v[160:161]
	s_waitcnt vmcnt(8)
	v_lshlrev_b32_e32 v160, 16, v142
	v_and_b32_e32 v161, 0xffff0000, v142
	v_lshlrev_b32_e32 v142, 16, v143
	v_and_b32_e32 v143, 0xffff0000, v143
	v_pk_add_f32 v[142:143], v[150:151], v[142:143]
	v_pk_add_f32 v[150:151], v[172:173], v[160:161]
	s_waitcnt vmcnt(7)
	v_lshlrev_b32_e32 v160, 16, v140
	v_and_b32_e32 v161, 0xffff0000, v140
	v_lshlrev_b32_e32 v140, 16, v141
	v_and_b32_e32 v141, 0xffff0000, v141
	v_pk_add_f32 v[158:159], v[176:177], v[158:159]
	v_pk_add_f32 v[148:149], v[148:149], v[140:141]
	s_waitcnt vmcnt(6)
	v_lshlrev_b32_e32 v140, 16, v136
	v_and_b32_e32 v141, 0xffff0000, v136
	v_pk_add_f32 v[168:169], v[170:171], v[160:161]
	v_pk_add_f32 v[170:171], v[158:159], v[140:141]
	s_waitcnt vmcnt(5)
	v_lshlrev_b32_e32 v140, 16, v138
	v_and_b32_e32 v141, 0xffff0000, v138
	v_lshlrev_b32_e32 v138, 16, v139
	v_and_b32_e32 v139, 0xffff0000, v139
	v_readlane_b32 s60, v254, 0
	v_pk_add_f32 v[146:147], v[146:147], v[138:139]
	s_waitcnt vmcnt(4)
	v_lshlrev_b32_e32 v138, 16, v134
	v_and_b32_e32 v139, 0xffff0000, v134
	v_lshlrev_b32_e32 v134, 16, v135
	v_and_b32_e32 v135, 0xffff0000, v135
	v_readlane_b32 s66, v254, 6
	v_readlane_b32 s67, v254, 7
	v_lshlrev_b32_e32 v136, 16, v137
	v_and_b32_e32 v137, 0xffff0000, v137
	v_pk_add_f32 v[134:135], v[142:143], v[134:135]
	v_lshl_add_u64 v[142:143], v[200:201], 2, s[66:67]
	v_pk_add_f32 v[136:137], v[144:145], v[136:137]
	v_pk_add_f32 v[172:173], v[152:153], v[140:141]
	v_pk_add_f32 v[174:175], v[150:151], v[138:139]
	global_load_dwordx4 v[150:153], v[142:143], off offset:16
	global_load_dwordx4 v[158:161], v[142:143], off
	global_load_dwordx4 v[138:141], v[142:143], off offset:528
	s_nop 0
	global_load_dwordx4 v[142:145], v[142:143], off offset:512
	s_waitcnt vmcnt(7)
	v_lshlrev_b32_e32 v176, 16, v132
	v_and_b32_e32 v177, 0xffff0000, v132
	v_lshlrev_b32_e32 v132, 16, v133
	v_and_b32_e32 v133, 0xffff0000, v133
	v_pk_add_f32 v[148:149], v[148:149], v[132:133]
	s_waitcnt vmcnt(6)
	v_lshlrev_b32_e32 v132, 16, v130
	v_and_b32_e32 v133, 0xffff0000, v130
	v_lshlrev_b32_e32 v130, 16, v131
	v_and_b32_e32 v131, 0xffff0000, v131
	v_pk_add_f32 v[168:169], v[168:169], v[176:177]
	v_pk_add_f32 v[170:171], v[170:171], v[132:133]
	v_pk_add_f32 v[176:177], v[136:137], v[130:131]
	s_waitcnt vmcnt(5)
	v_lshlrev_b32_e32 v130, 16, v154
	v_and_b32_e32 v131, 0xffff0000, v154
	v_lshlrev_b32_e32 v132, 16, v155
	v_and_b32_e32 v133, 0xffff0000, v155
	v_pk_fma_f32 v[132:133], v[146:147], 0.5, v[132:133] op_sel_hi:[1,0,1]
	v_pk_fma_f32 v[130:131], v[172:173], 0.5, v[130:131] op_sel_hi:[1,0,1]
	v_mul_f32_e32 v137, v133, v133
	v_mul_f32_e32 v136, v131, v131
	v_fmac_f32_e32 v136, v130, v130
	v_fmac_f32_e32 v137, v132, v132
	v_add_f32_e32 v154, v136, v137
	v_lshlrev_b32_e32 v146, 16, v156
	v_and_b32_e32 v147, 0xffff0000, v156
	v_lshlrev_b32_e32 v136, 16, v157
	v_and_b32_e32 v137, 0xffff0000, v157
	v_pk_fma_f32 v[136:137], v[134:135], 0.5, v[136:137] op_sel_hi:[1,0,1]
	v_pk_fma_f32 v[134:135], v[174:175], 0.5, v[146:147] op_sel_hi:[1,0,1]
	v_mul_f32_e32 v147, v137, v137
	v_mul_f32_e32 v146, v135, v135
	v_fmac_f32_e32 v146, v134, v134
	v_fmac_f32_e32 v147, v136, v136
	v_add_f32_e32 v146, v146, v147
	v_add_f32_e32 v156, v154, v146
	s_waitcnt vmcnt(4)
	v_lshlrev_b32_e32 v146, 16, v164
	v_and_b32_e32 v147, 0xffff0000, v164
	v_lshlrev_b32_e32 v154, 16, v165
	v_and_b32_e32 v155, 0xffff0000, v165
	v_pk_fma_f32 v[148:149], v[148:149], 0.5, v[154:155] op_sel_hi:[1,0,1]
	v_pk_fma_f32 v[146:147], v[168:169], 0.5, v[146:147] op_sel_hi:[1,0,1]
	v_mul_f32_e32 v155, v149, v149
	v_mul_f32_e32 v154, v147, v147
	v_fmac_f32_e32 v154, v146, v146
	v_fmac_f32_e32 v155, v148, v148
	v_add_f32_e32 v154, v154, v155
	v_add_f32_e32 v163, v156, v154
	v_lshlrev_b32_e32 v154, 16, v166
	v_and_b32_e32 v155, 0xffff0000, v166
	v_lshlrev_b32_e32 v156, 16, v167
	v_and_b32_e32 v157, 0xffff0000, v167
	v_pk_fma_f32 v[156:157], v[176:177], 0.5, v[156:157] op_sel_hi:[1,0,1]
	v_pk_fma_f32 v[154:155], v[170:171], 0.5, v[154:155] op_sel_hi:[1,0,1]
	v_mul_f32_e32 v165, v157, v157
	v_mul_f32_e32 v164, v155, v155
	v_fmac_f32_e32 v164, v154, v154
	v_fmac_f32_e32 v165, v156, v156
	v_add_f32_e32 v164, v164, v165
	v_and_b32_e32 v165, 64, v227
	v_add_f32_e32 v163, v163, v164
	v_xor_b32_e32 v164, 16, v227
	v_add_u32_e32 v165, 64, v165
	v_cmp_lt_i32_e32 vcc, v164, v165
	v_readlane_b32 s61, v254, 1
	v_readlane_b32 s62, v254, 2
	v_cndmask_b32_e32 v164, v227, v164, vcc
	v_lshlrev_b32_e32 v164, 2, v164
	ds_bpermute_b32 v164, v164, v163
	v_readlane_b32 s63, v254, 3
	v_readlane_b32 s64, v254, 4
	v_readlane_b32 s65, v254, 5
	s_waitcnt lgkmcnt(0)
	v_add_f32_e32 v163, v163, v164
	v_xor_b32_e32 v164, 32, v227
	v_cmp_lt_i32_e32 vcc, v164, v165
	s_nop 1
	v_cndmask_b32_e32 v164, v227, v164, vcc
	v_lshlrev_b32_e32 v164, 2, v164
	ds_bpermute_b32 v165, v164, v163
	v_or_b32_e32 v164, s36, v162
	s_and_saveexec_b64 s[58:59], s[10:11]
	s_cbranch_execz .LBB0_2147
	v_or_b32_e32 v162, s36, v162
	v_lshl_add_u32 v162, v162, 4, s93
	s_waitcnt lgkmcnt(0)
	v_add_f32_e32 v163, v163, v165
	ds_write_b32 v162, v163

	.amdhsa_kernel _Z6mk_fwd4Args
		.amdhsa_group_segment_fixed_size 0
		.amdhsa_private_segment_fixed_size 0
		.amdhsa_kernarg_size 504
		.amdhsa_user_sgpr_count 2
		.amdhsa_user_sgpr_dispatch_ptr 0
		.amdhsa_user_sgpr_queue_ptr 0
		.amdhsa_user_sgpr_kernarg_segment_ptr 1
		.amdhsa_user_sgpr_dispatch_id 0
		.amdhsa_user_sgpr_kernarg_preload_length 0
		.amdhsa_user_sgpr_kernarg_preload_offset 0
		.amdhsa_user_sgpr_private_segment_size 0
		.amdhsa_uses_dynamic_stack 0
		.amdhsa_enable_private_segment 0
		.amdhsa_system_sgpr_workgroup_id_x 1
		.amdhsa_system_sgpr_workgroup_id_y 0
		.amdhsa_system_sgpr_workgroup_id_z 0
		.amdhsa_system_sgpr_workgroup_info 0
		.amdhsa_system_vgpr_workitem_id 0
		.amdhsa_next_free_vgpr 256
		.amdhsa_next_free_sgpr 100
		.amdhsa_accum_offset 256
		.amdhsa_reserve_vcc 1
		.amdhsa_float_round_mode_32 0
		.amdhsa_float_round_mode_16_64 0
		.amdhsa_float_denorm_mode_32 3
		.amdhsa_float_denorm_mode_16_64 3
		.amdhsa_dx10_clamp 1
		.amdhsa_ieee_mode 1
		.amdhsa_fp16_overflow 0
		.amdhsa_tg_split 0
		.amdhsa_exception_fp_ieee_invalid_op 0
		.amdhsa_exception_fp_denorm_src 0
		.amdhsa_exception_fp_ieee_div_zero 0
		.amdhsa_exception_fp_ieee_overflow 0
		.amdhsa_exception_fp_ieee_underflow 0
		.amdhsa_exception_fp_ieee_inexact 0
		.amdhsa_exception_int_div_zero 0
	.end_amdhsa_kernel

amdhsa.kernels:
  - .agpr_count:     0
    .args:
      - .offset:         0
        .size:           248
        .value_kind:     by_value
      - .offset:         248
        .size:           4
        .value_kind:     hidden_block_count_x
      - .offset:         252
        .size:           4
        .value_kind:     hidden_block_count_y
      - .offset:         256
        .size:           4
        .value_kind:     hidden_block_count_z
      - .offset:         260
        .size:           2
        .value_kind:     hidden_group_size_x
      - .offset:         262
        .size:           2
        .value_kind:     hidden_group_size_y
      - .offset:         264
        .size:           2
        .value_kind:     hidden_group_size_z
      - .offset:         266
        .size:           2
        .value_kind:     hidden_remainder_x
      - .offset:         268
        .size:           2
        .value_kind:     hidden_remainder_y
      - .offset:         270
        .size:           2
        .value_kind:     hidden_remainder_z
      - .offset:         288
        .size:           8
        .value_kind:     hidden_global_offset_x
      - .offset:         296
        .size:           8
        .value_kind:     hidden_global_offset_y
      - .offset:         304
        .size:           8
        .value_kind:     hidden_global_offset_z
      - .offset:         312
        .size:           2
        .value_kind:     hidden_grid_dims
      - .offset:         368
        .size:           4
        .value_kind:     hidden_dynamic_lds_size
    .group_segment_fixed_size: 0
    .kernarg_segment_align: 8
    .kernarg_segment_size: 504
    .language:       OpenCL C
    .language_version:
      - 2
      - 0
    .max_flat_workgroup_size: 512
    .name:           _Z6mk_fwd4Args
    .private_segment_fixed_size: 0
    .sgpr_count:     106
    .sgpr_spill_count: 191
    .symbol:         _Z6mk_fwd4Args.kd
    .uniform_work_group_size: 1
    .uses_dynamic_stack: false
    .vgpr_count:     256
    .vgpr_spill_count: 0
    .wavefront_size: 64
